# scan inner loop hand-rescheduled: software-pipelined LDS operand refills, 16 steps unrolled, shorter reduction sequences
# baseline (speedup 1.0000x reference)
; DI float oct_sum(float v) { v += dpp_f<0xB1>(v); v += dpp_f<0x4E>(v); v += dpp_f<0x141>(v); return v; }
; DI void scan_item(const Params& p, int b, int h, int half, char* smem, unsigned* pgen, unsigned kp) {
;     ...
;     for (int sg = 0; sg < SC; sg += 4) {
;       float yy[4];
; #pragma unroll
;       for (int s4 = 0; s4 < 4; ++s4) {
;         const int s = sg + s4;
;         const f32x2* a2 = (const f32x2*)(Al + s * 64 + cg * 8);
;         const f32x2* w2 = (const f32x2*)(Wl + s * 64 + cg * 8);
;         const f32x2* b2 = (const f32x2*)(Bl + s * 64 + cg * 8);
;         const f32x2* k2 = (const f32x2*)(Kl + s * 64 + cg * 8);
;         const f32x2* r2 = (const f32x2*)(Rl + s * 64 + cg * 8);
;         f32x2 o[20];
; #pragma unroll
;         for (int i = 0; i < 4; ++i) { o[i] = a2[i]; o[4 + i] = w2[i]; o[8 + i] = b2[i]; o[12 + i] = k2[i]; o[16 + i] = r2[i]; }
;         const float vr = Vl[s * 64 + 32 * half + rp];
;         f32x2 p0 = St[0] * o[0], p1 = St[1] * o[1];
;         p0 = __builtin_elementwise_fma(St[2], o[2], p0); p1 = __builtin_elementwise_fma(St[3], o[3], p1);
;         const float sa = oct_sum((p0.x + p0.y) + (p1.x + p1.y));
;         const f32x2 sv = {sa, sa}, vv = {vr, vr};
;         f32x2 y0 = {0.f, 0.f}, y1 = {0.f, 0.f};
; #pragma unroll
;         for (int i = 0; i < 4; i += 2) {
;           St[i] = __builtin_elementwise_fma(St[i], o[4 + i], __builtin_elementwise_fma(sv, o[8 + i], vv * o[12 + i]));
;           St[i + 1] = __builtin_elementwise_fma(St[i + 1], o[5 + i], __builtin_elementwise_fma(sv, o[9 + i], vv * o[13 + i]));
;           y0 = __builtin_elementwise_fma(St[i], o[16 + i], y0);
;           y1 = __builtin_elementwise_fma(St[i + 1], o[17 + i], y1);
;         }
;         yy[s4] = oct_sum((y0.x + y0.y) + (y1.x + y1.y));
;       }
;       if (cg == 0) {
; #pragma unroll
;         for (int s4 = 0; s4 < 4; ++s4) Yl[(sg + s4) * 32 + rp] = yy[s4];
.LBB0_701:
	s_mov_b32 s26, -4
	v_mov_b32_e32 v0, v214
	v_mov_b32_e32 v161, v160
	v_mov_b32_e32 v162, v225
	ds_read_b128 v[34:37], v0 offset:16384
	ds_read_b128 v[38:41], v0 offset:16400
	ds_read_b128 v[68:71], v0 offset:8192
	ds_read_b128 v[150:153], v0 offset:8208
	ds_read2st64_b32 v[158:159], v161 offset0:0 offset1:1
	ds_read_b128 v[50:53], v0 offset:20480
	ds_read_b128 v[54:57], v0 offset:20496
	ds_read_b128 v[42:45], v0 offset:4096
	ds_read_b128 v[46:49], v0 offset:4112
	ds_read_b128 v[154:157], v0 offset:0
	ds_read_b128 v[246:249], v0 offset:16
	ds_read_b128 v[200:203], v0 offset:16640
	ds_read_b128 v[230:233], v0 offset:16656
	s_waitcnt lgkmcnt(11)
	v_pk_mul_f32 v[34:35], v[66:67], v[34:35]
	v_pk_mul_f32 v[36:37], v[64:65], v[36:37]
	v_pk_fma_f32 v[34:35], v[62:63], v[38:39], v[34:35]
	v_pk_fma_f32 v[36:37], v[60:61], v[40:41], v[36:37]
	v_add_f32_e32 v198, v34, v35
	v_add_f32_e32 v199, v36, v37
	v_add_f32_e32 v198, v198, v199
	s_waitcnt lgkmcnt(8)
	v_pk_mul_f32 v[58:59], v[68:69], v[158:159] op_sel_hi:[1,0]
	v_pk_mul_f32 v[72:73], v[70:71], v[158:159] op_sel_hi:[1,0]
	ds_read_b128 v[68:71], v0 offset:8448
	v_add_f32_dpp v198, v198, v198 quad_perm:[1,0,3,2] row_mask:0xf bank_mask:0xf bound_ctrl:1
	s_nop 0
	v_pk_mul_f32 v[212:213], v[150:151], v[158:159] op_sel_hi:[1,0]
	v_add_f32_dpp v198, v198, v198 quad_perm:[2,3,0,1] row_mask:0xf bank_mask:0xf bound_ctrl:1
	s_nop 0
	v_pk_mul_f32 v[250:251], v[152:153], v[158:159] op_sel_hi:[1,0]
	ds_read_b128 v[150:153], v0 offset:8464
	v_add_f32_dpp v198, v198, v198 row_half_mirror row_mask:0xf bank_mask:0xf bound_ctrl:1
	s_waitcnt lgkmcnt(8)
	v_pk_fma_f32 v[58:59], v[198:199], v[50:51], v[58:59] op_sel_hi:[0,1,1]
	v_pk_fma_f32 v[72:73], v[198:199], v[52:53], v[72:73] op_sel_hi:[0,1,1]
	s_waitcnt lgkmcnt(6)
	v_pk_fma_f32 v[66:67], v[66:67], v[42:43], v[58:59]
	v_pk_fma_f32 v[64:65], v[64:65], v[44:45], v[72:73]
	v_pk_fma_f32 v[212:213], v[198:199], v[54:55], v[212:213] op_sel_hi:[0,1,1]
	v_pk_fma_f32 v[250:251], v[198:199], v[56:57], v[250:251] op_sel_hi:[0,1,1]
	v_pk_fma_f32 v[62:63], v[62:63], v[46:47], v[212:213]
	v_pk_fma_f32 v[60:61], v[60:61], v[48:49], v[250:251]
	ds_read_b128 v[50:53], v0 offset:20736
	ds_read_b128 v[54:57], v0 offset:20752
	ds_read_b128 v[42:45], v0 offset:4352
	ds_read_b128 v[46:49], v0 offset:4368
	s_waitcnt lgkmcnt(8)
	v_pk_fma_f32 v[58:59], v[66:67], v[154:155], 0 op_sel_hi:[1,1,0]
	v_pk_fma_f32 v[72:73], v[64:65], v[156:157], 0 op_sel_hi:[1,1,0]
	v_pk_fma_f32 v[58:59], v[62:63], v[246:247], v[58:59]
	v_pk_fma_f32 v[72:73], v[60:61], v[248:249], v[72:73]
	ds_read_b128 v[154:157], v0 offset:256
	ds_read_b128 v[246:249], v0 offset:272
	v_add_f32_e32 v207, v58, v59
	v_add_f32_e32 v209, v72, v73
	ds_read_b128 v[34:37], v0 offset:16896
	ds_read_b128 v[38:41], v0 offset:16912
	s_waitcnt lgkmcnt(10)
	v_pk_mul_f32 v[200:201], v[66:67], v[200:201]
	v_pk_mul_f32 v[202:203], v[64:65], v[202:203]
	v_pk_fma_f32 v[200:201], v[62:63], v[230:231], v[200:201]
	v_pk_fma_f32 v[202:203], v[60:61], v[232:233], v[202:203]
	v_add_f32_e32 v198, v200, v201
	v_add_f32_e32 v199, v202, v203
	v_add_f32_e32 v207, v207, v209
	v_add_f32_e32 v198, v198, v199
	s_waitcnt lgkmcnt(8)
	v_mov_b32_e32 v232, v159
	v_pk_mul_f32 v[58:59], v[68:69], v[232:233] op_sel_hi:[1,0]
	v_pk_mul_f32 v[72:73], v[70:71], v[232:233] op_sel_hi:[1,0]
	ds_read_b128 v[68:71], v0 offset:8704
	v_add_f32_dpp v198, v198, v198 quad_perm:[1,0,3,2] row_mask:0xf bank_mask:0xf bound_ctrl:1
	v_add_f32_dpp v207, v207, v207 quad_perm:[1,0,3,2] row_mask:0xf bank_mask:0xf bound_ctrl:1
	v_pk_mul_f32 v[212:213], v[150:151], v[232:233] op_sel_hi:[1,0]
	v_add_f32_dpp v198, v198, v198 quad_perm:[2,3,0,1] row_mask:0xf bank_mask:0xf bound_ctrl:1
	v_add_f32_dpp v207, v207, v207 quad_perm:[2,3,0,1] row_mask:0xf bank_mask:0xf bound_ctrl:1
	v_pk_mul_f32 v[250:251], v[152:153], v[232:233] op_sel_hi:[1,0]
	ds_read_b128 v[150:153], v0 offset:8720
	v_add_f32_dpp v198, v198, v198 row_half_mirror row_mask:0xf bank_mask:0xf bound_ctrl:1
	v_add_f32_dpp v163, v207, v207 row_half_mirror row_mask:0xf bank_mask:0xf bound_ctrl:1
	ds_read2st64_b32 v[158:159], v161 offset0:2 offset1:3
	s_and_saveexec_b64 s[18:19], s[12:13]
	ds_write_b32 v162, v163 offset:0
	s_mov_b64 exec, s[18:19]
	s_waitcnt lgkmcnt(9)
	v_pk_fma_f32 v[58:59], v[198:199], v[50:51], v[58:59] op_sel_hi:[0,1,1]
	v_pk_fma_f32 v[72:73], v[198:199], v[52:53], v[72:73] op_sel_hi:[0,1,1]
	s_waitcnt lgkmcnt(7)
	v_pk_fma_f32 v[66:67], v[66:67], v[42:43], v[58:59]
	v_pk_fma_f32 v[64:65], v[64:65], v[44:45], v[72:73]
	v_pk_fma_f32 v[212:213], v[198:199], v[54:55], v[212:213] op_sel_hi:[0,1,1]
	v_pk_fma_f32 v[250:251], v[198:199], v[56:57], v[250:251] op_sel_hi:[0,1,1]
	v_pk_fma_f32 v[62:63], v[62:63], v[46:47], v[212:213]
	v_pk_fma_f32 v[60:61], v[60:61], v[48:49], v[250:251]
	ds_read_b128 v[50:53], v0 offset:20992
	ds_read_b128 v[54:57], v0 offset:21008
	ds_read_b128 v[42:45], v0 offset:4608
	ds_read_b128 v[46:49], v0 offset:4624
	s_waitcnt lgkmcnt(9)
	v_pk_fma_f32 v[58:59], v[66:67], v[154:155], 0 op_sel_hi:[1,1,0]
	v_pk_fma_f32 v[72:73], v[64:65], v[156:157], 0 op_sel_hi:[1,1,0]
	v_pk_fma_f32 v[58:59], v[62:63], v[246:247], v[58:59]
	v_pk_fma_f32 v[72:73], v[60:61], v[248:249], v[72:73]
	ds_read_b128 v[154:157], v0 offset:512
	ds_read_b128 v[246:249], v0 offset:528
	v_add_f32_e32 v207, v58, v59
	v_add_f32_e32 v209, v72, v73
	ds_read_b128 v[200:203], v0 offset:17152
	ds_read_b128 v[230:233], v0 offset:17168
	s_waitcnt lgkmcnt(11)
	v_pk_mul_f32 v[34:35], v[66:67], v[34:35]
	v_pk_mul_f32 v[36:37], v[64:65], v[36:37]
	v_pk_fma_f32 v[34:35], v[62:63], v[38:39], v[34:35]
	v_pk_fma_f32 v[36:37], v[60:61], v[40:41], v[36:37]
	v_add_f32_e32 v198, v34, v35
	v_add_f32_e32 v199, v36, v37
	v_add_f32_e32 v207, v207, v209
	v_add_f32_e32 v198, v198, v199
	s_waitcnt lgkmcnt(8)
; DI float oct_sum(float v) { v += dpp_f<0xB1>(v); v += dpp_f<0x4E>(v); v += dpp_f<0x141>(v); return v; }
; DI void scan_item(const Params& p, int b, int h, int half, char* smem, unsigned* pgen, unsigned kp) {
;     ...
;       for (int s4 = 0; s4 < 4; ++s4) {
;         const int s = sg + s4;
;         const f32x2* a2 = (const f32x2*)(Al + s * 64 + cg * 8);
;         const f32x2* w2 = (const f32x2*)(Wl + s * 64 + cg * 8);
;         const f32x2* b2 = (const f32x2*)(Bl + s * 64 + cg * 8);
;         const f32x2* k2 = (const f32x2*)(Kl + s * 64 + cg * 8);
;         const f32x2* r2 = (const f32x2*)(Rl + s * 64 + cg * 8);
;         f32x2 o[20];
; #pragma unroll
;         for (int i = 0; i < 4; ++i) { o[i] = a2[i]; o[4 + i] = w2[i]; o[8 + i] = b2[i]; o[12 + i] = k2[i]; o[16 + i] = r2[i]; }
;         const float vr = Vl[s * 64 + 32 * half + rp];
;         f32x2 p0 = St[0] * o[0], p1 = St[1] * o[1];
;         p0 = __builtin_elementwise_fma(St[2], o[2], p0); p1 = __builtin_elementwise_fma(St[3], o[3], p1);
;         const float sa = oct_sum((p0.x + p0.y) + (p1.x + p1.y));
;         const f32x2 sv = {sa, sa}, vv = {vr, vr};
;         f32x2 y0 = {0.f, 0.f}, y1 = {0.f, 0.f};
; #pragma unroll
;         for (int i = 0; i < 4; i += 2) {
;           St[i] = __builtin_elementwise_fma(St[i], o[4 + i], __builtin_elementwise_fma(sv, o[8 + i], vv * o[12 + i]));
;           St[i + 1] = __builtin_elementwise_fma(St[i + 1], o[5 + i], __builtin_elementwise_fma(sv, o[9 + i], vv * o[13 + i]));
;           y0 = __builtin_elementwise_fma(St[i], o[16 + i], y0);
;           y1 = __builtin_elementwise_fma(St[i + 1], o[17 + i], y1);
;         }
;         yy[s4] = oct_sum((y0.x + y0.y) + (y1.x + y1.y));
;       }
;       if (cg == 0) {
; #pragma unroll
;         for (int s4 = 0; s4 < 4; ++s4) Yl[(sg + s4) * 32 + rp] = yy[s4];
	v_pk_mul_f32 v[58:59], v[68:69], v[158:159] op_sel_hi:[1,0]
	v_pk_mul_f32 v[72:73], v[70:71], v[158:159] op_sel_hi:[1,0]
	ds_read_b128 v[68:71], v0 offset:8960
	v_add_f32_dpp v198, v198, v198 quad_perm:[1,0,3,2] row_mask:0xf bank_mask:0xf bound_ctrl:1
	v_add_f32_dpp v207, v207, v207 quad_perm:[1,0,3,2] row_mask:0xf bank_mask:0xf bound_ctrl:1
	v_pk_mul_f32 v[212:213], v[150:151], v[158:159] op_sel_hi:[1,0]
	v_add_f32_dpp v198, v198, v198 quad_perm:[2,3,0,1] row_mask:0xf bank_mask:0xf bound_ctrl:1
	v_add_f32_dpp v207, v207, v207 quad_perm:[2,3,0,1] row_mask:0xf bank_mask:0xf bound_ctrl:1
	v_pk_mul_f32 v[250:251], v[152:153], v[158:159] op_sel_hi:[1,0]
	ds_read_b128 v[150:153], v0 offset:8976
	v_add_f32_dpp v198, v198, v198 row_half_mirror row_mask:0xf bank_mask:0xf bound_ctrl:1
	v_add_f32_dpp v205, v207, v207 row_half_mirror row_mask:0xf bank_mask:0xf bound_ctrl:1
	s_and_saveexec_b64 s[18:19], s[12:13]
	ds_write_b32 v162, v205 offset:128
	s_mov_b64 exec, s[18:19]
	s_waitcnt lgkmcnt(8)
	v_pk_fma_f32 v[58:59], v[198:199], v[50:51], v[58:59] op_sel_hi:[0,1,1]
	v_pk_fma_f32 v[72:73], v[198:199], v[52:53], v[72:73] op_sel_hi:[0,1,1]
	s_waitcnt lgkmcnt(6)
	v_pk_fma_f32 v[66:67], v[66:67], v[42:43], v[58:59]
	v_pk_fma_f32 v[64:65], v[64:65], v[44:45], v[72:73]
	v_pk_fma_f32 v[212:213], v[198:199], v[54:55], v[212:213] op_sel_hi:[0,1,1]
	v_pk_fma_f32 v[250:251], v[198:199], v[56:57], v[250:251] op_sel_hi:[0,1,1]
	v_pk_fma_f32 v[62:63], v[62:63], v[46:47], v[212:213]
	v_pk_fma_f32 v[60:61], v[60:61], v[48:49], v[250:251]
	ds_read_b128 v[50:53], v0 offset:21248
	ds_read_b128 v[54:57], v0 offset:21264
	ds_read_b128 v[42:45], v0 offset:4864
	ds_read_b128 v[46:49], v0 offset:4880
	s_waitcnt lgkmcnt(8)
	v_pk_fma_f32 v[58:59], v[66:67], v[154:155], 0 op_sel_hi:[1,1,0]
	v_pk_fma_f32 v[72:73], v[64:65], v[156:157], 0 op_sel_hi:[1,1,0]
	v_pk_fma_f32 v[58:59], v[62:63], v[246:247], v[58:59]
	v_pk_fma_f32 v[72:73], v[60:61], v[248:249], v[72:73]
	ds_read_b128 v[154:157], v0 offset:768
	ds_read_b128 v[246:249], v0 offset:784
	v_add_f32_e32 v207, v58, v59
	v_add_f32_e32 v209, v72, v73
	ds_read_b128 v[34:37], v0 offset:17408
	ds_read_b128 v[38:41], v0 offset:17424
	s_waitcnt lgkmcnt(10)
	v_pk_mul_f32 v[200:201], v[66:67], v[200:201]
	v_pk_mul_f32 v[202:203], v[64:65], v[202:203]
	v_pk_fma_f32 v[200:201], v[62:63], v[230:231], v[200:201]
	v_pk_fma_f32 v[202:203], v[60:61], v[232:233], v[202:203]
	v_add_f32_e32 v198, v200, v201
	v_add_f32_e32 v199, v202, v203
	v_add_f32_e32 v207, v207, v209
	v_add_f32_e32 v198, v198, v199
	s_waitcnt lgkmcnt(8)
	v_mov_b32_e32 v232, v159
	v_pk_mul_f32 v[58:59], v[68:69], v[232:233] op_sel_hi:[1,0]
	v_pk_mul_f32 v[72:73], v[70:71], v[232:233] op_sel_hi:[1,0]
	ds_read_b128 v[68:71], v0 offset:9216
	v_add_f32_dpp v198, v198, v198 quad_perm:[1,0,3,2] row_mask:0xf bank_mask:0xf bound_ctrl:1
	v_add_f32_dpp v207, v207, v207 quad_perm:[1,0,3,2] row_mask:0xf bank_mask:0xf bound_ctrl:1
	v_pk_mul_f32 v[212:213], v[150:151], v[232:233] op_sel_hi:[1,0]
	v_add_f32_dpp v198, v198, v198 quad_perm:[2,3,0,1] row_mask:0xf bank_mask:0xf bound_ctrl:1
	v_add_f32_dpp v207, v207, v207 quad_perm:[2,3,0,1] row_mask:0xf bank_mask:0xf bound_ctrl:1
	v_pk_mul_f32 v[250:251], v[152:153], v[232:233] op_sel_hi:[1,0]
	ds_read_b128 v[150:153], v0 offset:9232
	v_add_f32_dpp v198, v198, v198 row_half_mirror row_mask:0xf bank_mask:0xf bound_ctrl:1
	v_add_f32_dpp v163, v207, v207 row_half_mirror row_mask:0xf bank_mask:0xf bound_ctrl:1
	ds_read2st64_b32 v[158:159], v161 offset0:4 offset1:5
	s_and_saveexec_b64 s[18:19], s[12:13]
	ds_write_b32 v162, v163 offset:256
	s_mov_b64 exec, s[18:19]
	s_waitcnt lgkmcnt(9)
	v_pk_fma_f32 v[58:59], v[198:199], v[50:51], v[58:59] op_sel_hi:[0,1,1]
	v_pk_fma_f32 v[72:73], v[198:199], v[52:53], v[72:73] op_sel_hi:[0,1,1]
	s_waitcnt lgkmcnt(7)
	v_pk_fma_f32 v[66:67], v[66:67], v[42:43], v[58:59]
	v_pk_fma_f32 v[64:65], v[64:65], v[44:45], v[72:73]
	v_pk_fma_f32 v[212:213], v[198:199], v[54:55], v[212:213] op_sel_hi:[0,1,1]
	v_pk_fma_f32 v[250:251], v[198:199], v[56:57], v[250:251] op_sel_hi:[0,1,1]
	v_pk_fma_f32 v[62:63], v[62:63], v[46:47], v[212:213]
	v_pk_fma_f32 v[60:61], v[60:61], v[48:49], v[250:251]
	ds_read_b128 v[50:53], v0 offset:21504
	ds_read_b128 v[54:57], v0 offset:21520
	ds_read_b128 v[42:45], v0 offset:5120
	ds_read_b128 v[46:49], v0 offset:5136
	s_waitcnt lgkmcnt(9)
	v_pk_fma_f32 v[58:59], v[66:67], v[154:155], 0 op_sel_hi:[1,1,0]
	v_pk_fma_f32 v[72:73], v[64:65], v[156:157], 0 op_sel_hi:[1,1,0]
	v_pk_fma_f32 v[58:59], v[62:63], v[246:247], v[58:59]
	v_pk_fma_f32 v[72:73], v[60:61], v[248:249], v[72:73]
	ds_read_b128 v[154:157], v0 offset:1024
	ds_read_b128 v[246:249], v0 offset:1040
	v_add_f32_e32 v207, v58, v59
	v_add_f32_e32 v209, v72, v73
	ds_read_b128 v[200:203], v0 offset:17664
	ds_read_b128 v[230:233], v0 offset:17680
	s_waitcnt lgkmcnt(11)
	v_pk_mul_f32 v[34:35], v[66:67], v[34:35]
	v_pk_mul_f32 v[36:37], v[64:65], v[36:37]
	v_pk_fma_f32 v[34:35], v[62:63], v[38:39], v[34:35]
	v_pk_fma_f32 v[36:37], v[60:61], v[40:41], v[36:37]
	v_add_f32_e32 v198, v34, v35
	v_add_f32_e32 v199, v36, v37
	v_add_f32_e32 v207, v207, v209
	v_add_f32_e32 v198, v198, v199
	s_waitcnt lgkmcnt(8)
; DI float oct_sum(float v) { v += dpp_f<0xB1>(v); v += dpp_f<0x4E>(v); v += dpp_f<0x141>(v); return v; }
; DI void scan_item(const Params& p, int b, int h, int half, char* smem, unsigned* pgen, unsigned kp) {
;     ...
;       for (int s4 = 0; s4 < 4; ++s4) {
;         const int s = sg + s4;
;         const f32x2* a2 = (const f32x2*)(Al + s * 64 + cg * 8);
;         const f32x2* w2 = (const f32x2*)(Wl + s * 64 + cg * 8);
;         const f32x2* b2 = (const f32x2*)(Bl + s * 64 + cg * 8);
;         const f32x2* k2 = (const f32x2*)(Kl + s * 64 + cg * 8);
;         const f32x2* r2 = (const f32x2*)(Rl + s * 64 + cg * 8);
;         f32x2 o[20];
; #pragma unroll
;         for (int i = 0; i < 4; ++i) { o[i] = a2[i]; o[4 + i] = w2[i]; o[8 + i] = b2[i]; o[12 + i] = k2[i]; o[16 + i] = r2[i]; }
;         const float vr = Vl[s * 64 + 32 * half + rp];
;         f32x2 p0 = St[0] * o[0], p1 = St[1] * o[1];
;         p0 = __builtin_elementwise_fma(St[2], o[2], p0); p1 = __builtin_elementwise_fma(St[3], o[3], p1);
;         const float sa = oct_sum((p0.x + p0.y) + (p1.x + p1.y));
;         const f32x2 sv = {sa, sa}, vv = {vr, vr};
;         f32x2 y0 = {0.f, 0.f}, y1 = {0.f, 0.f};
; #pragma unroll
;         for (int i = 0; i < 4; i += 2) {
;           St[i] = __builtin_elementwise_fma(St[i], o[4 + i], __builtin_elementwise_fma(sv, o[8 + i], vv * o[12 + i]));
;           St[i + 1] = __builtin_elementwise_fma(St[i + 1], o[5 + i], __builtin_elementwise_fma(sv, o[9 + i], vv * o[13 + i]));
;           y0 = __builtin_elementwise_fma(St[i], o[16 + i], y0);
;           y1 = __builtin_elementwise_fma(St[i + 1], o[17 + i], y1);
;         }
;         yy[s4] = oct_sum((y0.x + y0.y) + (y1.x + y1.y));
;       }
;       if (cg == 0) {
; #pragma unroll
;         for (int s4 = 0; s4 < 4; ++s4) Yl[(sg + s4) * 32 + rp] = yy[s4];
	v_pk_mul_f32 v[58:59], v[68:69], v[158:159] op_sel_hi:[1,0]
	v_pk_mul_f32 v[72:73], v[70:71], v[158:159] op_sel_hi:[1,0]
	ds_read_b128 v[68:71], v0 offset:9472
	v_add_f32_dpp v198, v198, v198 quad_perm:[1,0,3,2] row_mask:0xf bank_mask:0xf bound_ctrl:1
	v_add_f32_dpp v207, v207, v207 quad_perm:[1,0,3,2] row_mask:0xf bank_mask:0xf bound_ctrl:1
	v_pk_mul_f32 v[212:213], v[150:151], v[158:159] op_sel_hi:[1,0]
	v_add_f32_dpp v198, v198, v198 quad_perm:[2,3,0,1] row_mask:0xf bank_mask:0xf bound_ctrl:1
	v_add_f32_dpp v207, v207, v207 quad_perm:[2,3,0,1] row_mask:0xf bank_mask:0xf bound_ctrl:1
	v_pk_mul_f32 v[250:251], v[152:153], v[158:159] op_sel_hi:[1,0]
	ds_read_b128 v[150:153], v0 offset:9488
	v_add_f32_dpp v198, v198, v198 row_half_mirror row_mask:0xf bank_mask:0xf bound_ctrl:1
	v_add_f32_dpp v205, v207, v207 row_half_mirror row_mask:0xf bank_mask:0xf bound_ctrl:1
	s_and_saveexec_b64 s[18:19], s[12:13]
	ds_write_b32 v162, v205 offset:384
	s_mov_b64 exec, s[18:19]
	s_waitcnt lgkmcnt(8)
	v_pk_fma_f32 v[58:59], v[198:199], v[50:51], v[58:59] op_sel_hi:[0,1,1]
	v_pk_fma_f32 v[72:73], v[198:199], v[52:53], v[72:73] op_sel_hi:[0,1,1]
	s_waitcnt lgkmcnt(6)
	v_pk_fma_f32 v[66:67], v[66:67], v[42:43], v[58:59]
	v_pk_fma_f32 v[64:65], v[64:65], v[44:45], v[72:73]
	v_pk_fma_f32 v[212:213], v[198:199], v[54:55], v[212:213] op_sel_hi:[0,1,1]
	v_pk_fma_f32 v[250:251], v[198:199], v[56:57], v[250:251] op_sel_hi:[0,1,1]
	v_pk_fma_f32 v[62:63], v[62:63], v[46:47], v[212:213]
	v_pk_fma_f32 v[60:61], v[60:61], v[48:49], v[250:251]
	ds_read_b128 v[50:53], v0 offset:21760
	ds_read_b128 v[54:57], v0 offset:21776
	ds_read_b128 v[42:45], v0 offset:5376
	ds_read_b128 v[46:49], v0 offset:5392
	s_waitcnt lgkmcnt(8)
	v_pk_fma_f32 v[58:59], v[66:67], v[154:155], 0 op_sel_hi:[1,1,0]
	v_pk_fma_f32 v[72:73], v[64:65], v[156:157], 0 op_sel_hi:[1,1,0]
	v_pk_fma_f32 v[58:59], v[62:63], v[246:247], v[58:59]
	v_pk_fma_f32 v[72:73], v[60:61], v[248:249], v[72:73]
	ds_read_b128 v[154:157], v0 offset:1280
	ds_read_b128 v[246:249], v0 offset:1296
	v_add_f32_e32 v207, v58, v59
	v_add_f32_e32 v209, v72, v73
	ds_read_b128 v[34:37], v0 offset:17920
	ds_read_b128 v[38:41], v0 offset:17936
	s_waitcnt lgkmcnt(10)
	v_pk_mul_f32 v[200:201], v[66:67], v[200:201]
	v_pk_mul_f32 v[202:203], v[64:65], v[202:203]
	v_pk_fma_f32 v[200:201], v[62:63], v[230:231], v[200:201]
	v_pk_fma_f32 v[202:203], v[60:61], v[232:233], v[202:203]
	v_add_f32_e32 v198, v200, v201
	v_add_f32_e32 v199, v202, v203
	v_add_f32_e32 v207, v207, v209
	v_add_f32_e32 v198, v198, v199
	s_waitcnt lgkmcnt(8)
	v_mov_b32_e32 v232, v159
	v_pk_mul_f32 v[58:59], v[68:69], v[232:233] op_sel_hi:[1,0]
	v_pk_mul_f32 v[72:73], v[70:71], v[232:233] op_sel_hi:[1,0]
	ds_read_b128 v[68:71], v0 offset:9728
	v_add_f32_dpp v198, v198, v198 quad_perm:[1,0,3,2] row_mask:0xf bank_mask:0xf bound_ctrl:1
	v_add_f32_dpp v207, v207, v207 quad_perm:[1,0,3,2] row_mask:0xf bank_mask:0xf bound_ctrl:1
	v_pk_mul_f32 v[212:213], v[150:151], v[232:233] op_sel_hi:[1,0]
	v_add_f32_dpp v198, v198, v198 quad_perm:[2,3,0,1] row_mask:0xf bank_mask:0xf bound_ctrl:1
	v_add_f32_dpp v207, v207, v207 quad_perm:[2,3,0,1] row_mask:0xf bank_mask:0xf bound_ctrl:1
	v_pk_mul_f32 v[250:251], v[152:153], v[232:233] op_sel_hi:[1,0]
	ds_read_b128 v[150:153], v0 offset:9744
	v_add_f32_dpp v198, v198, v198 row_half_mirror row_mask:0xf bank_mask:0xf bound_ctrl:1
	v_add_f32_dpp v163, v207, v207 row_half_mirror row_mask:0xf bank_mask:0xf bound_ctrl:1
	ds_read2st64_b32 v[158:159], v161 offset0:6 offset1:7
	s_and_saveexec_b64 s[18:19], s[12:13]
	ds_write_b32 v162, v163 offset:512
	s_mov_b64 exec, s[18:19]
	s_waitcnt lgkmcnt(9)
	v_pk_fma_f32 v[58:59], v[198:199], v[50:51], v[58:59] op_sel_hi:[0,1,1]
	v_pk_fma_f32 v[72:73], v[198:199], v[52:53], v[72:73] op_sel_hi:[0,1,1]
	s_waitcnt lgkmcnt(7)
	v_pk_fma_f32 v[66:67], v[66:67], v[42:43], v[58:59]
	v_pk_fma_f32 v[64:65], v[64:65], v[44:45], v[72:73]
	v_pk_fma_f32 v[212:213], v[198:199], v[54:55], v[212:213] op_sel_hi:[0,1,1]
	v_pk_fma_f32 v[250:251], v[198:199], v[56:57], v[250:251] op_sel_hi:[0,1,1]
	v_pk_fma_f32 v[62:63], v[62:63], v[46:47], v[212:213]
	v_pk_fma_f32 v[60:61], v[60:61], v[48:49], v[250:251]
	ds_read_b128 v[50:53], v0 offset:22016
	ds_read_b128 v[54:57], v0 offset:22032
	ds_read_b128 v[42:45], v0 offset:5632
	ds_read_b128 v[46:49], v0 offset:5648
	s_waitcnt lgkmcnt(9)
	v_pk_fma_f32 v[58:59], v[66:67], v[154:155], 0 op_sel_hi:[1,1,0]
	v_pk_fma_f32 v[72:73], v[64:65], v[156:157], 0 op_sel_hi:[1,1,0]
	v_pk_fma_f32 v[58:59], v[62:63], v[246:247], v[58:59]
	v_pk_fma_f32 v[72:73], v[60:61], v[248:249], v[72:73]
	ds_read_b128 v[154:157], v0 offset:1536
	ds_read_b128 v[246:249], v0 offset:1552
	v_add_f32_e32 v207, v58, v59
	v_add_f32_e32 v209, v72, v73
	ds_read_b128 v[200:203], v0 offset:18176
	ds_read_b128 v[230:233], v0 offset:18192
	s_waitcnt lgkmcnt(11)
	v_pk_mul_f32 v[34:35], v[66:67], v[34:35]
	v_pk_mul_f32 v[36:37], v[64:65], v[36:37]
	v_pk_fma_f32 v[34:35], v[62:63], v[38:39], v[34:35]
	v_pk_fma_f32 v[36:37], v[60:61], v[40:41], v[36:37]
	v_add_f32_e32 v198, v34, v35
	v_add_f32_e32 v199, v36, v37
	v_add_f32_e32 v207, v207, v209
	v_add_f32_e32 v198, v198, v199
	s_waitcnt lgkmcnt(8)
; DI float oct_sum(float v) { v += dpp_f<0xB1>(v); v += dpp_f<0x4E>(v); v += dpp_f<0x141>(v); return v; }
; DI void scan_item(const Params& p, int b, int h, int half, char* smem, unsigned* pgen, unsigned kp) {
;     ...
;       for (int s4 = 0; s4 < 4; ++s4) {
;         const int s = sg + s4;
;         const f32x2* a2 = (const f32x2*)(Al + s * 64 + cg * 8);
;         const f32x2* w2 = (const f32x2*)(Wl + s * 64 + cg * 8);
;         const f32x2* b2 = (const f32x2*)(Bl + s * 64 + cg * 8);
;         const f32x2* k2 = (const f32x2*)(Kl + s * 64 + cg * 8);
;         const f32x2* r2 = (const f32x2*)(Rl + s * 64 + cg * 8);
;         f32x2 o[20];
; #pragma unroll
;         for (int i = 0; i < 4; ++i) { o[i] = a2[i]; o[4 + i] = w2[i]; o[8 + i] = b2[i]; o[12 + i] = k2[i]; o[16 + i] = r2[i]; }
;         const float vr = Vl[s * 64 + 32 * half + rp];
;         f32x2 p0 = St[0] * o[0], p1 = St[1] * o[1];
;         p0 = __builtin_elementwise_fma(St[2], o[2], p0); p1 = __builtin_elementwise_fma(St[3], o[3], p1);
;         const float sa = oct_sum((p0.x + p0.y) + (p1.x + p1.y));
;         const f32x2 sv = {sa, sa}, vv = {vr, vr};
;         f32x2 y0 = {0.f, 0.f}, y1 = {0.f, 0.f};
; #pragma unroll
;         for (int i = 0; i < 4; i += 2) {
;           St[i] = __builtin_elementwise_fma(St[i], o[4 + i], __builtin_elementwise_fma(sv, o[8 + i], vv * o[12 + i]));
;           St[i + 1] = __builtin_elementwise_fma(St[i + 1], o[5 + i], __builtin_elementwise_fma(sv, o[9 + i], vv * o[13 + i]));
;           y0 = __builtin_elementwise_fma(St[i], o[16 + i], y0);
;           y1 = __builtin_elementwise_fma(St[i + 1], o[17 + i], y1);
;         }
;         yy[s4] = oct_sum((y0.x + y0.y) + (y1.x + y1.y));
;       }
;       if (cg == 0) {
; #pragma unroll
;         for (int s4 = 0; s4 < 4; ++s4) Yl[(sg + s4) * 32 + rp] = yy[s4];
	v_pk_mul_f32 v[58:59], v[68:69], v[158:159] op_sel_hi:[1,0]
	v_pk_mul_f32 v[72:73], v[70:71], v[158:159] op_sel_hi:[1,0]
	ds_read_b128 v[68:71], v0 offset:9984
	v_add_f32_dpp v198, v198, v198 quad_perm:[1,0,3,2] row_mask:0xf bank_mask:0xf bound_ctrl:1
	v_add_f32_dpp v207, v207, v207 quad_perm:[1,0,3,2] row_mask:0xf bank_mask:0xf bound_ctrl:1
	v_pk_mul_f32 v[212:213], v[150:151], v[158:159] op_sel_hi:[1,0]
	v_add_f32_dpp v198, v198, v198 quad_perm:[2,3,0,1] row_mask:0xf bank_mask:0xf bound_ctrl:1
	v_add_f32_dpp v207, v207, v207 quad_perm:[2,3,0,1] row_mask:0xf bank_mask:0xf bound_ctrl:1
	v_pk_mul_f32 v[250:251], v[152:153], v[158:159] op_sel_hi:[1,0]
	ds_read_b128 v[150:153], v0 offset:10000
	v_add_f32_dpp v198, v198, v198 row_half_mirror row_mask:0xf bank_mask:0xf bound_ctrl:1
	v_add_f32_dpp v205, v207, v207 row_half_mirror row_mask:0xf bank_mask:0xf bound_ctrl:1
	s_and_saveexec_b64 s[18:19], s[12:13]
	ds_write_b32 v162, v205 offset:640
	s_mov_b64 exec, s[18:19]
	s_waitcnt lgkmcnt(8)
	v_pk_fma_f32 v[58:59], v[198:199], v[50:51], v[58:59] op_sel_hi:[0,1,1]
	v_pk_fma_f32 v[72:73], v[198:199], v[52:53], v[72:73] op_sel_hi:[0,1,1]
	s_waitcnt lgkmcnt(6)
	v_pk_fma_f32 v[66:67], v[66:67], v[42:43], v[58:59]
	v_pk_fma_f32 v[64:65], v[64:65], v[44:45], v[72:73]
	v_pk_fma_f32 v[212:213], v[198:199], v[54:55], v[212:213] op_sel_hi:[0,1,1]
	v_pk_fma_f32 v[250:251], v[198:199], v[56:57], v[250:251] op_sel_hi:[0,1,1]
	v_pk_fma_f32 v[62:63], v[62:63], v[46:47], v[212:213]
	v_pk_fma_f32 v[60:61], v[60:61], v[48:49], v[250:251]
	ds_read_b128 v[50:53], v0 offset:22272
	ds_read_b128 v[54:57], v0 offset:22288
	ds_read_b128 v[42:45], v0 offset:5888
	ds_read_b128 v[46:49], v0 offset:5904
	s_waitcnt lgkmcnt(8)
	v_pk_fma_f32 v[58:59], v[66:67], v[154:155], 0 op_sel_hi:[1,1,0]
	v_pk_fma_f32 v[72:73], v[64:65], v[156:157], 0 op_sel_hi:[1,1,0]
	v_pk_fma_f32 v[58:59], v[62:63], v[246:247], v[58:59]
	v_pk_fma_f32 v[72:73], v[60:61], v[248:249], v[72:73]
	ds_read_b128 v[154:157], v0 offset:1792
	ds_read_b128 v[246:249], v0 offset:1808
	v_add_f32_e32 v207, v58, v59
	v_add_f32_e32 v209, v72, v73
	ds_read_b128 v[34:37], v0 offset:18432
	ds_read_b128 v[38:41], v0 offset:18448
	s_waitcnt lgkmcnt(10)
	v_pk_mul_f32 v[200:201], v[66:67], v[200:201]
	v_pk_mul_f32 v[202:203], v[64:65], v[202:203]
	v_pk_fma_f32 v[200:201], v[62:63], v[230:231], v[200:201]
	v_pk_fma_f32 v[202:203], v[60:61], v[232:233], v[202:203]
	v_add_f32_e32 v198, v200, v201
	v_add_f32_e32 v199, v202, v203
	v_add_f32_e32 v207, v207, v209
	v_add_f32_e32 v198, v198, v199
	s_waitcnt lgkmcnt(8)
	v_mov_b32_e32 v232, v159
	v_pk_mul_f32 v[58:59], v[68:69], v[232:233] op_sel_hi:[1,0]
	v_pk_mul_f32 v[72:73], v[70:71], v[232:233] op_sel_hi:[1,0]
	ds_read_b128 v[68:71], v0 offset:10240
	v_add_f32_dpp v198, v198, v198 quad_perm:[1,0,3,2] row_mask:0xf bank_mask:0xf bound_ctrl:1
	v_add_f32_dpp v207, v207, v207 quad_perm:[1,0,3,2] row_mask:0xf bank_mask:0xf bound_ctrl:1
	v_pk_mul_f32 v[212:213], v[150:151], v[232:233] op_sel_hi:[1,0]
	v_add_f32_dpp v198, v198, v198 quad_perm:[2,3,0,1] row_mask:0xf bank_mask:0xf bound_ctrl:1
	v_add_f32_dpp v207, v207, v207 quad_perm:[2,3,0,1] row_mask:0xf bank_mask:0xf bound_ctrl:1
	v_pk_mul_f32 v[250:251], v[152:153], v[232:233] op_sel_hi:[1,0]
	ds_read_b128 v[150:153], v0 offset:10256
	v_add_f32_dpp v198, v198, v198 row_half_mirror row_mask:0xf bank_mask:0xf bound_ctrl:1
	v_add_f32_dpp v163, v207, v207 row_half_mirror row_mask:0xf bank_mask:0xf bound_ctrl:1
	ds_read2st64_b32 v[158:159], v161 offset0:8 offset1:9
	s_and_saveexec_b64 s[18:19], s[12:13]
	ds_write_b32 v162, v163 offset:768
	s_mov_b64 exec, s[18:19]
	s_waitcnt lgkmcnt(9)
	v_pk_fma_f32 v[58:59], v[198:199], v[50:51], v[58:59] op_sel_hi:[0,1,1]
	v_pk_fma_f32 v[72:73], v[198:199], v[52:53], v[72:73] op_sel_hi:[0,1,1]
	s_waitcnt lgkmcnt(7)
	v_pk_fma_f32 v[66:67], v[66:67], v[42:43], v[58:59]
	v_pk_fma_f32 v[64:65], v[64:65], v[44:45], v[72:73]
	v_pk_fma_f32 v[212:213], v[198:199], v[54:55], v[212:213] op_sel_hi:[0,1,1]
	v_pk_fma_f32 v[250:251], v[198:199], v[56:57], v[250:251] op_sel_hi:[0,1,1]
	v_pk_fma_f32 v[62:63], v[62:63], v[46:47], v[212:213]
	v_pk_fma_f32 v[60:61], v[60:61], v[48:49], v[250:251]
	ds_read_b128 v[50:53], v0 offset:22528
	ds_read_b128 v[54:57], v0 offset:22544
	ds_read_b128 v[42:45], v0 offset:6144
	ds_read_b128 v[46:49], v0 offset:6160
	s_waitcnt lgkmcnt(9)
	v_pk_fma_f32 v[58:59], v[66:67], v[154:155], 0 op_sel_hi:[1,1,0]
	v_pk_fma_f32 v[72:73], v[64:65], v[156:157], 0 op_sel_hi:[1,1,0]
	v_pk_fma_f32 v[58:59], v[62:63], v[246:247], v[58:59]
	v_pk_fma_f32 v[72:73], v[60:61], v[248:249], v[72:73]
	ds_read_b128 v[154:157], v0 offset:2048
	ds_read_b128 v[246:249], v0 offset:2064
	v_add_f32_e32 v207, v58, v59
	v_add_f32_e32 v209, v72, v73
	ds_read_b128 v[200:203], v0 offset:18688
	ds_read_b128 v[230:233], v0 offset:18704
	s_waitcnt lgkmcnt(11)
	v_pk_mul_f32 v[34:35], v[66:67], v[34:35]
	v_pk_mul_f32 v[36:37], v[64:65], v[36:37]
	v_pk_fma_f32 v[34:35], v[62:63], v[38:39], v[34:35]
	v_pk_fma_f32 v[36:37], v[60:61], v[40:41], v[36:37]
	v_add_f32_e32 v198, v34, v35
	v_add_f32_e32 v199, v36, v37
	v_add_f32_e32 v207, v207, v209
	v_add_f32_e32 v198, v198, v199
	s_waitcnt lgkmcnt(8)
; DI float oct_sum(float v) { v += dpp_f<0xB1>(v); v += dpp_f<0x4E>(v); v += dpp_f<0x141>(v); return v; }
; DI void scan_item(const Params& p, int b, int h, int half, char* smem, unsigned* pgen, unsigned kp) {
;     ...
;       for (int s4 = 0; s4 < 4; ++s4) {
;         const int s = sg + s4;
;         const f32x2* a2 = (const f32x2*)(Al + s * 64 + cg * 8);
;         const f32x2* w2 = (const f32x2*)(Wl + s * 64 + cg * 8);
;         const f32x2* b2 = (const f32x2*)(Bl + s * 64 + cg * 8);
;         const f32x2* k2 = (const f32x2*)(Kl + s * 64 + cg * 8);
;         const f32x2* r2 = (const f32x2*)(Rl + s * 64 + cg * 8);
;         f32x2 o[20];
; #pragma unroll
;         for (int i = 0; i < 4; ++i) { o[i] = a2[i]; o[4 + i] = w2[i]; o[8 + i] = b2[i]; o[12 + i] = k2[i]; o[16 + i] = r2[i]; }
;         const float vr = Vl[s * 64 + 32 * half + rp];
;         f32x2 p0 = St[0] * o[0], p1 = St[1] * o[1];
;         p0 = __builtin_elementwise_fma(St[2], o[2], p0); p1 = __builtin_elementwise_fma(St[3], o[3], p1);
;         const float sa = oct_sum((p0.x + p0.y) + (p1.x + p1.y));
;         const f32x2 sv = {sa, sa}, vv = {vr, vr};
;         f32x2 y0 = {0.f, 0.f}, y1 = {0.f, 0.f};
; #pragma unroll
;         for (int i = 0; i < 4; i += 2) {
;           St[i] = __builtin_elementwise_fma(St[i], o[4 + i], __builtin_elementwise_fma(sv, o[8 + i], vv * o[12 + i]));
;           St[i + 1] = __builtin_elementwise_fma(St[i + 1], o[5 + i], __builtin_elementwise_fma(sv, o[9 + i], vv * o[13 + i]));
;           y0 = __builtin_elementwise_fma(St[i], o[16 + i], y0);
;           y1 = __builtin_elementwise_fma(St[i + 1], o[17 + i], y1);
;         }
;         yy[s4] = oct_sum((y0.x + y0.y) + (y1.x + y1.y));
;       }
;       if (cg == 0) {
; #pragma unroll
;         for (int s4 = 0; s4 < 4; ++s4) Yl[(sg + s4) * 32 + rp] = yy[s4];
	v_pk_mul_f32 v[58:59], v[68:69], v[158:159] op_sel_hi:[1,0]
	v_pk_mul_f32 v[72:73], v[70:71], v[158:159] op_sel_hi:[1,0]
	ds_read_b128 v[68:71], v0 offset:10496
	v_add_f32_dpp v198, v198, v198 quad_perm:[1,0,3,2] row_mask:0xf bank_mask:0xf bound_ctrl:1
	v_add_f32_dpp v207, v207, v207 quad_perm:[1,0,3,2] row_mask:0xf bank_mask:0xf bound_ctrl:1
	v_pk_mul_f32 v[212:213], v[150:151], v[158:159] op_sel_hi:[1,0]
	v_add_f32_dpp v198, v198, v198 quad_perm:[2,3,0,1] row_mask:0xf bank_mask:0xf bound_ctrl:1
	v_add_f32_dpp v207, v207, v207 quad_perm:[2,3,0,1] row_mask:0xf bank_mask:0xf bound_ctrl:1
	v_pk_mul_f32 v[250:251], v[152:153], v[158:159] op_sel_hi:[1,0]
	ds_read_b128 v[150:153], v0 offset:10512
	v_add_f32_dpp v198, v198, v198 row_half_mirror row_mask:0xf bank_mask:0xf bound_ctrl:1
	v_add_f32_dpp v205, v207, v207 row_half_mirror row_mask:0xf bank_mask:0xf bound_ctrl:1
	s_and_saveexec_b64 s[18:19], s[12:13]
	ds_write_b32 v162, v205 offset:896
	s_mov_b64 exec, s[18:19]
	s_waitcnt lgkmcnt(8)
	v_pk_fma_f32 v[58:59], v[198:199], v[50:51], v[58:59] op_sel_hi:[0,1,1]
	v_pk_fma_f32 v[72:73], v[198:199], v[52:53], v[72:73] op_sel_hi:[0,1,1]
	s_waitcnt lgkmcnt(6)
	v_pk_fma_f32 v[66:67], v[66:67], v[42:43], v[58:59]
	v_pk_fma_f32 v[64:65], v[64:65], v[44:45], v[72:73]
	v_pk_fma_f32 v[212:213], v[198:199], v[54:55], v[212:213] op_sel_hi:[0,1,1]
	v_pk_fma_f32 v[250:251], v[198:199], v[56:57], v[250:251] op_sel_hi:[0,1,1]
	v_pk_fma_f32 v[62:63], v[62:63], v[46:47], v[212:213]
	v_pk_fma_f32 v[60:61], v[60:61], v[48:49], v[250:251]
	ds_read_b128 v[50:53], v0 offset:22784
	ds_read_b128 v[54:57], v0 offset:22800
	ds_read_b128 v[42:45], v0 offset:6400
	ds_read_b128 v[46:49], v0 offset:6416
	s_waitcnt lgkmcnt(8)
	v_pk_fma_f32 v[58:59], v[66:67], v[154:155], 0 op_sel_hi:[1,1,0]
	v_pk_fma_f32 v[72:73], v[64:65], v[156:157], 0 op_sel_hi:[1,1,0]
	v_pk_fma_f32 v[58:59], v[62:63], v[246:247], v[58:59]
	v_pk_fma_f32 v[72:73], v[60:61], v[248:249], v[72:73]
	ds_read_b128 v[154:157], v0 offset:2304
	ds_read_b128 v[246:249], v0 offset:2320
	v_add_f32_e32 v207, v58, v59
	v_add_f32_e32 v209, v72, v73
	ds_read_b128 v[34:37], v0 offset:18944
	ds_read_b128 v[38:41], v0 offset:18960
	s_waitcnt lgkmcnt(10)
	v_pk_mul_f32 v[200:201], v[66:67], v[200:201]
	v_pk_mul_f32 v[202:203], v[64:65], v[202:203]
	v_pk_fma_f32 v[200:201], v[62:63], v[230:231], v[200:201]
	v_pk_fma_f32 v[202:203], v[60:61], v[232:233], v[202:203]
	v_add_f32_e32 v198, v200, v201
	v_add_f32_e32 v199, v202, v203
	v_add_f32_e32 v207, v207, v209
	v_add_f32_e32 v198, v198, v199
	s_waitcnt lgkmcnt(8)
	v_mov_b32_e32 v232, v159
	v_pk_mul_f32 v[58:59], v[68:69], v[232:233] op_sel_hi:[1,0]
	v_pk_mul_f32 v[72:73], v[70:71], v[232:233] op_sel_hi:[1,0]
	ds_read_b128 v[68:71], v0 offset:10752
	v_add_f32_dpp v198, v198, v198 quad_perm:[1,0,3,2] row_mask:0xf bank_mask:0xf bound_ctrl:1
	v_add_f32_dpp v207, v207, v207 quad_perm:[1,0,3,2] row_mask:0xf bank_mask:0xf bound_ctrl:1
	v_pk_mul_f32 v[212:213], v[150:151], v[232:233] op_sel_hi:[1,0]
	v_add_f32_dpp v198, v198, v198 quad_perm:[2,3,0,1] row_mask:0xf bank_mask:0xf bound_ctrl:1
	v_add_f32_dpp v207, v207, v207 quad_perm:[2,3,0,1] row_mask:0xf bank_mask:0xf bound_ctrl:1
	v_pk_mul_f32 v[250:251], v[152:153], v[232:233] op_sel_hi:[1,0]
	ds_read_b128 v[150:153], v0 offset:10768
	v_add_f32_dpp v198, v198, v198 row_half_mirror row_mask:0xf bank_mask:0xf bound_ctrl:1
	v_add_f32_dpp v163, v207, v207 row_half_mirror row_mask:0xf bank_mask:0xf bound_ctrl:1
	ds_read2st64_b32 v[158:159], v161 offset0:10 offset1:11
	s_and_saveexec_b64 s[18:19], s[12:13]
	ds_write_b32 v162, v163 offset:1024
	s_mov_b64 exec, s[18:19]
	s_waitcnt lgkmcnt(9)
	v_pk_fma_f32 v[58:59], v[198:199], v[50:51], v[58:59] op_sel_hi:[0,1,1]
	v_pk_fma_f32 v[72:73], v[198:199], v[52:53], v[72:73] op_sel_hi:[0,1,1]
	s_waitcnt lgkmcnt(7)
	v_pk_fma_f32 v[66:67], v[66:67], v[42:43], v[58:59]
	v_pk_fma_f32 v[64:65], v[64:65], v[44:45], v[72:73]
	v_pk_fma_f32 v[212:213], v[198:199], v[54:55], v[212:213] op_sel_hi:[0,1,1]
	v_pk_fma_f32 v[250:251], v[198:199], v[56:57], v[250:251] op_sel_hi:[0,1,1]
	v_pk_fma_f32 v[62:63], v[62:63], v[46:47], v[212:213]
	v_pk_fma_f32 v[60:61], v[60:61], v[48:49], v[250:251]
	ds_read_b128 v[50:53], v0 offset:23040
	ds_read_b128 v[54:57], v0 offset:23056
	ds_read_b128 v[42:45], v0 offset:6656
	ds_read_b128 v[46:49], v0 offset:6672
	s_waitcnt lgkmcnt(9)
	v_pk_fma_f32 v[58:59], v[66:67], v[154:155], 0 op_sel_hi:[1,1,0]
	v_pk_fma_f32 v[72:73], v[64:65], v[156:157], 0 op_sel_hi:[1,1,0]
	v_pk_fma_f32 v[58:59], v[62:63], v[246:247], v[58:59]
	v_pk_fma_f32 v[72:73], v[60:61], v[248:249], v[72:73]
	ds_read_b128 v[154:157], v0 offset:2560
	ds_read_b128 v[246:249], v0 offset:2576
	v_add_f32_e32 v207, v58, v59
	v_add_f32_e32 v209, v72, v73
	ds_read_b128 v[200:203], v0 offset:19200
	ds_read_b128 v[230:233], v0 offset:19216
	s_waitcnt lgkmcnt(11)
	v_pk_mul_f32 v[34:35], v[66:67], v[34:35]
	v_pk_mul_f32 v[36:37], v[64:65], v[36:37]
	v_pk_fma_f32 v[34:35], v[62:63], v[38:39], v[34:35]
	v_pk_fma_f32 v[36:37], v[60:61], v[40:41], v[36:37]
	v_add_f32_e32 v198, v34, v35
	v_add_f32_e32 v199, v36, v37
	v_add_f32_e32 v207, v207, v209
	v_add_f32_e32 v198, v198, v199
	s_waitcnt lgkmcnt(8)
; DI float oct_sum(float v) { v += dpp_f<0xB1>(v); v += dpp_f<0x4E>(v); v += dpp_f<0x141>(v); return v; }
; DI void scan_item(const Params& p, int b, int h, int half, char* smem, unsigned* pgen, unsigned kp) {
;     ...
;       for (int s4 = 0; s4 < 4; ++s4) {
;         const int s = sg + s4;
;         const f32x2* a2 = (const f32x2*)(Al + s * 64 + cg * 8);
;         const f32x2* w2 = (const f32x2*)(Wl + s * 64 + cg * 8);
;         const f32x2* b2 = (const f32x2*)(Bl + s * 64 + cg * 8);
;         const f32x2* k2 = (const f32x2*)(Kl + s * 64 + cg * 8);
;         const f32x2* r2 = (const f32x2*)(Rl + s * 64 + cg * 8);
;         f32x2 o[20];
; #pragma unroll
;         for (int i = 0; i < 4; ++i) { o[i] = a2[i]; o[4 + i] = w2[i]; o[8 + i] = b2[i]; o[12 + i] = k2[i]; o[16 + i] = r2[i]; }
;         const float vr = Vl[s * 64 + 32 * half + rp];
;         f32x2 p0 = St[0] * o[0], p1 = St[1] * o[1];
;         p0 = __builtin_elementwise_fma(St[2], o[2], p0); p1 = __builtin_elementwise_fma(St[3], o[3], p1);
;         const float sa = oct_sum((p0.x + p0.y) + (p1.x + p1.y));
;         const f32x2 sv = {sa, sa}, vv = {vr, vr};
;         f32x2 y0 = {0.f, 0.f}, y1 = {0.f, 0.f};
; #pragma unroll
;         for (int i = 0; i < 4; i += 2) {
;           St[i] = __builtin_elementwise_fma(St[i], o[4 + i], __builtin_elementwise_fma(sv, o[8 + i], vv * o[12 + i]));
;           St[i + 1] = __builtin_elementwise_fma(St[i + 1], o[5 + i], __builtin_elementwise_fma(sv, o[9 + i], vv * o[13 + i]));
;           y0 = __builtin_elementwise_fma(St[i], o[16 + i], y0);
;           y1 = __builtin_elementwise_fma(St[i + 1], o[17 + i], y1);
;         }
;         yy[s4] = oct_sum((y0.x + y0.y) + (y1.x + y1.y));
;       }
;       if (cg == 0) {
; #pragma unroll
;         for (int s4 = 0; s4 < 4; ++s4) Yl[(sg + s4) * 32 + rp] = yy[s4];
	v_pk_mul_f32 v[58:59], v[68:69], v[158:159] op_sel_hi:[1,0]
	v_pk_mul_f32 v[72:73], v[70:71], v[158:159] op_sel_hi:[1,0]
	ds_read_b128 v[68:71], v0 offset:11008
	v_add_f32_dpp v198, v198, v198 quad_perm:[1,0,3,2] row_mask:0xf bank_mask:0xf bound_ctrl:1
	v_add_f32_dpp v207, v207, v207 quad_perm:[1,0,3,2] row_mask:0xf bank_mask:0xf bound_ctrl:1
	v_pk_mul_f32 v[212:213], v[150:151], v[158:159] op_sel_hi:[1,0]
	v_add_f32_dpp v198, v198, v198 quad_perm:[2,3,0,1] row_mask:0xf bank_mask:0xf bound_ctrl:1
	v_add_f32_dpp v207, v207, v207 quad_perm:[2,3,0,1] row_mask:0xf bank_mask:0xf bound_ctrl:1
	v_pk_mul_f32 v[250:251], v[152:153], v[158:159] op_sel_hi:[1,0]
	ds_read_b128 v[150:153], v0 offset:11024
	v_add_f32_dpp v198, v198, v198 row_half_mirror row_mask:0xf bank_mask:0xf bound_ctrl:1
	v_add_f32_dpp v205, v207, v207 row_half_mirror row_mask:0xf bank_mask:0xf bound_ctrl:1
	s_and_saveexec_b64 s[18:19], s[12:13]
	ds_write_b32 v162, v205 offset:1152
	s_mov_b64 exec, s[18:19]
	s_waitcnt lgkmcnt(8)
	v_pk_fma_f32 v[58:59], v[198:199], v[50:51], v[58:59] op_sel_hi:[0,1,1]
	v_pk_fma_f32 v[72:73], v[198:199], v[52:53], v[72:73] op_sel_hi:[0,1,1]
	s_waitcnt lgkmcnt(6)
	v_pk_fma_f32 v[66:67], v[66:67], v[42:43], v[58:59]
	v_pk_fma_f32 v[64:65], v[64:65], v[44:45], v[72:73]
	v_pk_fma_f32 v[212:213], v[198:199], v[54:55], v[212:213] op_sel_hi:[0,1,1]
	v_pk_fma_f32 v[250:251], v[198:199], v[56:57], v[250:251] op_sel_hi:[0,1,1]
	v_pk_fma_f32 v[62:63], v[62:63], v[46:47], v[212:213]
	v_pk_fma_f32 v[60:61], v[60:61], v[48:49], v[250:251]
	ds_read_b128 v[50:53], v0 offset:23296
	ds_read_b128 v[54:57], v0 offset:23312
	ds_read_b128 v[42:45], v0 offset:6912
	ds_read_b128 v[46:49], v0 offset:6928
	s_waitcnt lgkmcnt(8)
	v_pk_fma_f32 v[58:59], v[66:67], v[154:155], 0 op_sel_hi:[1,1,0]
	v_pk_fma_f32 v[72:73], v[64:65], v[156:157], 0 op_sel_hi:[1,1,0]
	v_pk_fma_f32 v[58:59], v[62:63], v[246:247], v[58:59]
	v_pk_fma_f32 v[72:73], v[60:61], v[248:249], v[72:73]
	ds_read_b128 v[154:157], v0 offset:2816
	ds_read_b128 v[246:249], v0 offset:2832
	v_add_f32_e32 v207, v58, v59
	v_add_f32_e32 v209, v72, v73
	ds_read_b128 v[34:37], v0 offset:19456
	ds_read_b128 v[38:41], v0 offset:19472
	s_waitcnt lgkmcnt(10)
	v_pk_mul_f32 v[200:201], v[66:67], v[200:201]
	v_pk_mul_f32 v[202:203], v[64:65], v[202:203]
	v_pk_fma_f32 v[200:201], v[62:63], v[230:231], v[200:201]
	v_pk_fma_f32 v[202:203], v[60:61], v[232:233], v[202:203]
	v_add_f32_e32 v198, v200, v201
	v_add_f32_e32 v199, v202, v203
	v_add_f32_e32 v207, v207, v209
	v_add_f32_e32 v198, v198, v199
	s_waitcnt lgkmcnt(8)
	v_mov_b32_e32 v232, v159
	v_pk_mul_f32 v[58:59], v[68:69], v[232:233] op_sel_hi:[1,0]
	v_pk_mul_f32 v[72:73], v[70:71], v[232:233] op_sel_hi:[1,0]
	ds_read_b128 v[68:71], v0 offset:11264
	v_add_f32_dpp v198, v198, v198 quad_perm:[1,0,3,2] row_mask:0xf bank_mask:0xf bound_ctrl:1
	v_add_f32_dpp v207, v207, v207 quad_perm:[1,0,3,2] row_mask:0xf bank_mask:0xf bound_ctrl:1
	v_pk_mul_f32 v[212:213], v[150:151], v[232:233] op_sel_hi:[1,0]
	v_add_f32_dpp v198, v198, v198 quad_perm:[2,3,0,1] row_mask:0xf bank_mask:0xf bound_ctrl:1
	v_add_f32_dpp v207, v207, v207 quad_perm:[2,3,0,1] row_mask:0xf bank_mask:0xf bound_ctrl:1
	v_pk_mul_f32 v[250:251], v[152:153], v[232:233] op_sel_hi:[1,0]
	ds_read_b128 v[150:153], v0 offset:11280
	v_add_f32_dpp v198, v198, v198 row_half_mirror row_mask:0xf bank_mask:0xf bound_ctrl:1
	v_add_f32_dpp v163, v207, v207 row_half_mirror row_mask:0xf bank_mask:0xf bound_ctrl:1
	ds_read2st64_b32 v[158:159], v161 offset0:12 offset1:13
	s_and_saveexec_b64 s[18:19], s[12:13]
	ds_write_b32 v162, v163 offset:1280
	s_mov_b64 exec, s[18:19]
	s_waitcnt lgkmcnt(9)
	v_pk_fma_f32 v[58:59], v[198:199], v[50:51], v[58:59] op_sel_hi:[0,1,1]
	v_pk_fma_f32 v[72:73], v[198:199], v[52:53], v[72:73] op_sel_hi:[0,1,1]
	s_waitcnt lgkmcnt(7)
	v_pk_fma_f32 v[66:67], v[66:67], v[42:43], v[58:59]
	v_pk_fma_f32 v[64:65], v[64:65], v[44:45], v[72:73]
	v_pk_fma_f32 v[212:213], v[198:199], v[54:55], v[212:213] op_sel_hi:[0,1,1]
	v_pk_fma_f32 v[250:251], v[198:199], v[56:57], v[250:251] op_sel_hi:[0,1,1]
	v_pk_fma_f32 v[62:63], v[62:63], v[46:47], v[212:213]
	v_pk_fma_f32 v[60:61], v[60:61], v[48:49], v[250:251]
	ds_read_b128 v[50:53], v0 offset:23552
	ds_read_b128 v[54:57], v0 offset:23568
	ds_read_b128 v[42:45], v0 offset:7168
	ds_read_b128 v[46:49], v0 offset:7184
	s_waitcnt lgkmcnt(9)
	v_pk_fma_f32 v[58:59], v[66:67], v[154:155], 0 op_sel_hi:[1,1,0]
	v_pk_fma_f32 v[72:73], v[64:65], v[156:157], 0 op_sel_hi:[1,1,0]
	v_pk_fma_f32 v[58:59], v[62:63], v[246:247], v[58:59]
	v_pk_fma_f32 v[72:73], v[60:61], v[248:249], v[72:73]
	ds_read_b128 v[154:157], v0 offset:3072
	ds_read_b128 v[246:249], v0 offset:3088
	v_add_f32_e32 v207, v58, v59
	v_add_f32_e32 v209, v72, v73
	ds_read_b128 v[200:203], v0 offset:19712
	ds_read_b128 v[230:233], v0 offset:19728
	s_waitcnt lgkmcnt(11)
	v_pk_mul_f32 v[34:35], v[66:67], v[34:35]
	v_pk_mul_f32 v[36:37], v[64:65], v[36:37]
	v_pk_fma_f32 v[34:35], v[62:63], v[38:39], v[34:35]
	v_pk_fma_f32 v[36:37], v[60:61], v[40:41], v[36:37]
	v_add_f32_e32 v198, v34, v35
	v_add_f32_e32 v199, v36, v37
	v_add_f32_e32 v207, v207, v209
	v_add_f32_e32 v198, v198, v199
	s_waitcnt lgkmcnt(8)
; DI float oct_sum(float v) { v += dpp_f<0xB1>(v); v += dpp_f<0x4E>(v); v += dpp_f<0x141>(v); return v; }
; DI void scan_item(const Params& p, int b, int h, int half, char* smem, unsigned* pgen, unsigned kp) {
;     ...
; #pragma unroll 1
;     for (int sg = 0; sg < SC; sg += 4) {
;       float yy[4];
; #pragma unroll
;       for (int s4 = 0; s4 < 4; ++s4) {
;         const int s = sg + s4;
;         const f32x2* a2 = (const f32x2*)(Al + s * 64 + cg * 8);
;         const f32x2* w2 = (const f32x2*)(Wl + s * 64 + cg * 8);
;         const f32x2* b2 = (const f32x2*)(Bl + s * 64 + cg * 8);
;         const f32x2* k2 = (const f32x2*)(Kl + s * 64 + cg * 8);
;         const f32x2* r2 = (const f32x2*)(Rl + s * 64 + cg * 8);
;         f32x2 o[20];
; #pragma unroll
;         for (int i = 0; i < 4; ++i) { o[i] = a2[i]; o[4 + i] = w2[i]; o[8 + i] = b2[i]; o[12 + i] = k2[i]; o[16 + i] = r2[i]; }
;         const float vr = Vl[s * 64 + 32 * half + rp];
;         f32x2 p0 = St[0] * o[0], p1 = St[1] * o[1];
;         p0 = __builtin_elementwise_fma(St[2], o[2], p0); p1 = __builtin_elementwise_fma(St[3], o[3], p1);
;         const float sa = oct_sum((p0.x + p0.y) + (p1.x + p1.y));
;         const f32x2 sv = {sa, sa}, vv = {vr, vr};
;         f32x2 y0 = {0.f, 0.f}, y1 = {0.f, 0.f};
; #pragma unroll
;         for (int i = 0; i < 4; i += 2) {
;           St[i] = __builtin_elementwise_fma(St[i], o[4 + i], __builtin_elementwise_fma(sv, o[8 + i], vv * o[12 + i]));
;           St[i + 1] = __builtin_elementwise_fma(St[i + 1], o[5 + i], __builtin_elementwise_fma(sv, o[9 + i], vv * o[13 + i]));
;           y0 = __builtin_elementwise_fma(St[i], o[16 + i], y0);
;           y1 = __builtin_elementwise_fma(St[i + 1], o[17 + i], y1);
;         }
;         yy[s4] = oct_sum((y0.x + y0.y) + (y1.x + y1.y));
;       }
;       if (cg == 0) {
; #pragma unroll
;         for (int s4 = 0; s4 < 4; ++s4) Yl[(sg + s4) * 32 + rp] = yy[s4];
;       }
	v_pk_mul_f32 v[58:59], v[68:69], v[158:159] op_sel_hi:[1,0]
	v_pk_mul_f32 v[72:73], v[70:71], v[158:159] op_sel_hi:[1,0]
	ds_read_b128 v[68:71], v0 offset:11520
	v_add_f32_dpp v198, v198, v198 quad_perm:[1,0,3,2] row_mask:0xf bank_mask:0xf bound_ctrl:1
	v_add_f32_dpp v207, v207, v207 quad_perm:[1,0,3,2] row_mask:0xf bank_mask:0xf bound_ctrl:1
	v_pk_mul_f32 v[212:213], v[150:151], v[158:159] op_sel_hi:[1,0]
	v_add_f32_dpp v198, v198, v198 quad_perm:[2,3,0,1] row_mask:0xf bank_mask:0xf bound_ctrl:1
	v_add_f32_dpp v207, v207, v207 quad_perm:[2,3,0,1] row_mask:0xf bank_mask:0xf bound_ctrl:1
	v_pk_mul_f32 v[250:251], v[152:153], v[158:159] op_sel_hi:[1,0]
	ds_read_b128 v[150:153], v0 offset:11536
	v_add_f32_dpp v198, v198, v198 row_half_mirror row_mask:0xf bank_mask:0xf bound_ctrl:1
	v_add_f32_dpp v205, v207, v207 row_half_mirror row_mask:0xf bank_mask:0xf bound_ctrl:1
	s_and_saveexec_b64 s[18:19], s[12:13]
	ds_write_b32 v162, v205 offset:1408
	s_mov_b64 exec, s[18:19]
	s_waitcnt lgkmcnt(8)
	v_pk_fma_f32 v[58:59], v[198:199], v[50:51], v[58:59] op_sel_hi:[0,1,1]
	v_pk_fma_f32 v[72:73], v[198:199], v[52:53], v[72:73] op_sel_hi:[0,1,1]
	s_waitcnt lgkmcnt(6)
	v_pk_fma_f32 v[66:67], v[66:67], v[42:43], v[58:59]
	v_pk_fma_f32 v[64:65], v[64:65], v[44:45], v[72:73]
	v_pk_fma_f32 v[212:213], v[198:199], v[54:55], v[212:213] op_sel_hi:[0,1,1]
	v_pk_fma_f32 v[250:251], v[198:199], v[56:57], v[250:251] op_sel_hi:[0,1,1]
	v_pk_fma_f32 v[62:63], v[62:63], v[46:47], v[212:213]
	v_pk_fma_f32 v[60:61], v[60:61], v[48:49], v[250:251]
	ds_read_b128 v[50:53], v0 offset:23808
	ds_read_b128 v[54:57], v0 offset:23824
	ds_read_b128 v[42:45], v0 offset:7424
	ds_read_b128 v[46:49], v0 offset:7440
	s_waitcnt lgkmcnt(8)
	v_pk_fma_f32 v[58:59], v[66:67], v[154:155], 0 op_sel_hi:[1,1,0]
	v_pk_fma_f32 v[72:73], v[64:65], v[156:157], 0 op_sel_hi:[1,1,0]
	v_pk_fma_f32 v[58:59], v[62:63], v[246:247], v[58:59]
	v_pk_fma_f32 v[72:73], v[60:61], v[248:249], v[72:73]
	ds_read_b128 v[154:157], v0 offset:3328
	ds_read_b128 v[246:249], v0 offset:3344
	v_add_f32_e32 v207, v58, v59
	v_add_f32_e32 v209, v72, v73
	ds_read_b128 v[34:37], v0 offset:19968
	ds_read_b128 v[38:41], v0 offset:19984
	s_waitcnt lgkmcnt(10)
	v_pk_mul_f32 v[200:201], v[66:67], v[200:201]
	v_pk_mul_f32 v[202:203], v[64:65], v[202:203]
	v_pk_fma_f32 v[200:201], v[62:63], v[230:231], v[200:201]
	v_pk_fma_f32 v[202:203], v[60:61], v[232:233], v[202:203]
	v_add_f32_e32 v198, v200, v201
	v_add_f32_e32 v199, v202, v203
	v_add_f32_e32 v207, v207, v209
	v_add_f32_e32 v198, v198, v199
	s_waitcnt lgkmcnt(8)
	v_mov_b32_e32 v232, v159
	v_pk_mul_f32 v[58:59], v[68:69], v[232:233] op_sel_hi:[1,0]
	v_pk_mul_f32 v[72:73], v[70:71], v[232:233] op_sel_hi:[1,0]
	ds_read_b128 v[68:71], v0 offset:11776
	v_add_f32_dpp v198, v198, v198 quad_perm:[1,0,3,2] row_mask:0xf bank_mask:0xf bound_ctrl:1
	v_add_f32_dpp v207, v207, v207 quad_perm:[1,0,3,2] row_mask:0xf bank_mask:0xf bound_ctrl:1
	v_pk_mul_f32 v[212:213], v[150:151], v[232:233] op_sel_hi:[1,0]
	v_add_f32_dpp v198, v198, v198 quad_perm:[2,3,0,1] row_mask:0xf bank_mask:0xf bound_ctrl:1
	v_add_f32_dpp v207, v207, v207 quad_perm:[2,3,0,1] row_mask:0xf bank_mask:0xf bound_ctrl:1
	v_pk_mul_f32 v[250:251], v[152:153], v[232:233] op_sel_hi:[1,0]
	ds_read_b128 v[150:153], v0 offset:11792
	v_add_f32_dpp v198, v198, v198 row_half_mirror row_mask:0xf bank_mask:0xf bound_ctrl:1
	v_add_f32_dpp v163, v207, v207 row_half_mirror row_mask:0xf bank_mask:0xf bound_ctrl:1
	ds_read2st64_b32 v[158:159], v161 offset0:14 offset1:15
	s_and_saveexec_b64 s[18:19], s[12:13]
	ds_write_b32 v162, v163 offset:1536
	s_mov_b64 exec, s[18:19]
	s_waitcnt lgkmcnt(9)
	v_pk_fma_f32 v[58:59], v[198:199], v[50:51], v[58:59] op_sel_hi:[0,1,1]
	v_pk_fma_f32 v[72:73], v[198:199], v[52:53], v[72:73] op_sel_hi:[0,1,1]
	s_waitcnt lgkmcnt(7)
	v_pk_fma_f32 v[66:67], v[66:67], v[42:43], v[58:59]
	v_pk_fma_f32 v[64:65], v[64:65], v[44:45], v[72:73]
	v_pk_fma_f32 v[212:213], v[198:199], v[54:55], v[212:213] op_sel_hi:[0,1,1]
	v_pk_fma_f32 v[250:251], v[198:199], v[56:57], v[250:251] op_sel_hi:[0,1,1]
	v_pk_fma_f32 v[62:63], v[62:63], v[46:47], v[212:213]
	v_pk_fma_f32 v[60:61], v[60:61], v[48:49], v[250:251]
	ds_read_b128 v[50:53], v0 offset:24064
	ds_read_b128 v[54:57], v0 offset:24080
	ds_read_b128 v[42:45], v0 offset:7680
	ds_read_b128 v[46:49], v0 offset:7696
	s_waitcnt lgkmcnt(9)
	v_pk_fma_f32 v[58:59], v[66:67], v[154:155], 0 op_sel_hi:[1,1,0]
	v_pk_fma_f32 v[72:73], v[64:65], v[156:157], 0 op_sel_hi:[1,1,0]
	v_pk_fma_f32 v[58:59], v[62:63], v[246:247], v[58:59]
	v_pk_fma_f32 v[72:73], v[60:61], v[248:249], v[72:73]
	ds_read_b128 v[154:157], v0 offset:3584
	ds_read_b128 v[246:249], v0 offset:3600
	v_add_f32_e32 v207, v58, v59
	v_add_f32_e32 v209, v72, v73
	ds_read_b128 v[200:203], v0 offset:20224
	ds_read_b128 v[230:233], v0 offset:20240
	s_waitcnt lgkmcnt(11)
; DI float oct_sum(float v) { v += dpp_f<0xB1>(v); v += dpp_f<0x4E>(v); v += dpp_f<0x141>(v); return v; }
; DI void scan_item(const Params& p, int b, int h, int half, char* smem, unsigned* pgen, unsigned kp) {
;     ...
; #pragma unroll 1
;     for (int sg = 0; sg < SC; sg += 4) {
;       float yy[4];
; #pragma unroll
;       for (int s4 = 0; s4 < 4; ++s4) {
;         const int s = sg + s4;
;         const f32x2* a2 = (const f32x2*)(Al + s * 64 + cg * 8);
;         const f32x2* w2 = (const f32x2*)(Wl + s * 64 + cg * 8);
;         const f32x2* b2 = (const f32x2*)(Bl + s * 64 + cg * 8);
;         const f32x2* k2 = (const f32x2*)(Kl + s * 64 + cg * 8);
;         const f32x2* r2 = (const f32x2*)(Rl + s * 64 + cg * 8);
;         f32x2 o[20];
; #pragma unroll
;         for (int i = 0; i < 4; ++i) { o[i] = a2[i]; o[4 + i] = w2[i]; o[8 + i] = b2[i]; o[12 + i] = k2[i]; o[16 + i] = r2[i]; }
;         const float vr = Vl[s * 64 + 32 * half + rp];
;         f32x2 p0 = St[0] * o[0], p1 = St[1] * o[1];
;         p0 = __builtin_elementwise_fma(St[2], o[2], p0); p1 = __builtin_elementwise_fma(St[3], o[3], p1);
;         const float sa = oct_sum((p0.x + p0.y) + (p1.x + p1.y));
;         const f32x2 sv = {sa, sa}, vv = {vr, vr};
;         f32x2 y0 = {0.f, 0.f}, y1 = {0.f, 0.f};
; #pragma unroll
;         for (int i = 0; i < 4; i += 2) {
;           St[i] = __builtin_elementwise_fma(St[i], o[4 + i], __builtin_elementwise_fma(sv, o[8 + i], vv * o[12 + i]));
;           St[i + 1] = __builtin_elementwise_fma(St[i + 1], o[5 + i], __builtin_elementwise_fma(sv, o[9 + i], vv * o[13 + i]));
;           y0 = __builtin_elementwise_fma(St[i], o[16 + i], y0);
;           y1 = __builtin_elementwise_fma(St[i + 1], o[17 + i], y1);
;         }
;         yy[s4] = oct_sum((y0.x + y0.y) + (y1.x + y1.y));
;       }
;       if (cg == 0) {
; #pragma unroll
;         for (int s4 = 0; s4 < 4; ++s4) Yl[(sg + s4) * 32 + rp] = yy[s4];
;       }
	v_pk_mul_f32 v[34:35], v[66:67], v[34:35]
	v_pk_mul_f32 v[36:37], v[64:65], v[36:37]
	v_pk_fma_f32 v[34:35], v[62:63], v[38:39], v[34:35]
	v_pk_fma_f32 v[36:37], v[60:61], v[40:41], v[36:37]
	v_add_f32_e32 v198, v34, v35
	v_add_f32_e32 v199, v36, v37
	v_add_f32_e32 v207, v207, v209
	v_add_f32_e32 v198, v198, v199
	s_waitcnt lgkmcnt(8)
	v_pk_mul_f32 v[58:59], v[68:69], v[158:159] op_sel_hi:[1,0]
	v_pk_mul_f32 v[72:73], v[70:71], v[158:159] op_sel_hi:[1,0]
	ds_read_b128 v[68:71], v0 offset:12032
	v_add_f32_dpp v198, v198, v198 quad_perm:[1,0,3,2] row_mask:0xf bank_mask:0xf bound_ctrl:1
	v_add_f32_dpp v207, v207, v207 quad_perm:[1,0,3,2] row_mask:0xf bank_mask:0xf bound_ctrl:1
	v_pk_mul_f32 v[212:213], v[150:151], v[158:159] op_sel_hi:[1,0]
	v_add_f32_dpp v198, v198, v198 quad_perm:[2,3,0,1] row_mask:0xf bank_mask:0xf bound_ctrl:1
	v_add_f32_dpp v207, v207, v207 quad_perm:[2,3,0,1] row_mask:0xf bank_mask:0xf bound_ctrl:1
	v_pk_mul_f32 v[250:251], v[152:153], v[158:159] op_sel_hi:[1,0]
	ds_read_b128 v[150:153], v0 offset:12048
	v_add_f32_dpp v198, v198, v198 row_half_mirror row_mask:0xf bank_mask:0xf bound_ctrl:1
	v_add_f32_dpp v205, v207, v207 row_half_mirror row_mask:0xf bank_mask:0xf bound_ctrl:1
	s_and_saveexec_b64 s[18:19], s[12:13]
	ds_write_b32 v162, v205 offset:1664
	s_mov_b64 exec, s[18:19]
	s_waitcnt lgkmcnt(8)
	v_pk_fma_f32 v[58:59], v[198:199], v[50:51], v[58:59] op_sel_hi:[0,1,1]
	v_pk_fma_f32 v[72:73], v[198:199], v[52:53], v[72:73] op_sel_hi:[0,1,1]
	s_waitcnt lgkmcnt(6)
	v_pk_fma_f32 v[66:67], v[66:67], v[42:43], v[58:59]
	v_pk_fma_f32 v[64:65], v[64:65], v[44:45], v[72:73]
	v_pk_fma_f32 v[212:213], v[198:199], v[54:55], v[212:213] op_sel_hi:[0,1,1]
	v_pk_fma_f32 v[250:251], v[198:199], v[56:57], v[250:251] op_sel_hi:[0,1,1]
	v_pk_fma_f32 v[62:63], v[62:63], v[46:47], v[212:213]
	v_pk_fma_f32 v[60:61], v[60:61], v[48:49], v[250:251]
	ds_read_b128 v[50:53], v0 offset:24320
	ds_read_b128 v[54:57], v0 offset:24336
	ds_read_b128 v[42:45], v0 offset:7936
	ds_read_b128 v[46:49], v0 offset:7952
	s_waitcnt lgkmcnt(8)
	v_pk_fma_f32 v[58:59], v[66:67], v[154:155], 0 op_sel_hi:[1,1,0]
	v_pk_fma_f32 v[72:73], v[64:65], v[156:157], 0 op_sel_hi:[1,1,0]
	v_pk_fma_f32 v[58:59], v[62:63], v[246:247], v[58:59]
	v_pk_fma_f32 v[72:73], v[60:61], v[248:249], v[72:73]
	ds_read_b128 v[154:157], v0 offset:3840
	ds_read_b128 v[246:249], v0 offset:3856
	v_add_f32_e32 v207, v58, v59
	v_add_f32_e32 v209, v72, v73
	s_waitcnt lgkmcnt(8)
	v_pk_mul_f32 v[200:201], v[66:67], v[200:201]
	v_pk_mul_f32 v[202:203], v[64:65], v[202:203]
	v_pk_fma_f32 v[200:201], v[62:63], v[230:231], v[200:201]
	v_pk_fma_f32 v[202:203], v[60:61], v[232:233], v[202:203]
	v_add_f32_e32 v198, v200, v201
	v_add_f32_e32 v199, v202, v203
	v_add_f32_e32 v207, v207, v209
	v_add_f32_e32 v198, v198, v199
	s_waitcnt lgkmcnt(6)
	v_mov_b32_e32 v232, v159
	v_pk_mul_f32 v[58:59], v[68:69], v[232:233] op_sel_hi:[1,0]
	v_pk_mul_f32 v[72:73], v[70:71], v[232:233] op_sel_hi:[1,0]
	v_add_f32_dpp v198, v198, v198 quad_perm:[1,0,3,2] row_mask:0xf bank_mask:0xf bound_ctrl:1
	v_add_f32_dpp v207, v207, v207 quad_perm:[1,0,3,2] row_mask:0xf bank_mask:0xf bound_ctrl:1
	v_pk_mul_f32 v[212:213], v[150:151], v[232:233] op_sel_hi:[1,0]
	v_add_f32_dpp v198, v198, v198 quad_perm:[2,3,0,1] row_mask:0xf bank_mask:0xf bound_ctrl:1
	v_add_f32_dpp v207, v207, v207 quad_perm:[2,3,0,1] row_mask:0xf bank_mask:0xf bound_ctrl:1
	v_pk_mul_f32 v[250:251], v[152:153], v[232:233] op_sel_hi:[1,0]
	v_add_f32_dpp v198, v198, v198 row_half_mirror row_mask:0xf bank_mask:0xf bound_ctrl:1
	v_add_f32_dpp v163, v207, v207 row_half_mirror row_mask:0xf bank_mask:0xf bound_ctrl:1
	s_and_saveexec_b64 s[18:19], s[12:13]
	ds_write_b32 v162, v163 offset:1792
	s_mov_b64 exec, s[18:19]
	s_waitcnt lgkmcnt(4)
	v_pk_fma_f32 v[58:59], v[198:199], v[50:51], v[58:59] op_sel_hi:[0,1,1]
	v_pk_fma_f32 v[72:73], v[198:199], v[52:53], v[72:73] op_sel_hi:[0,1,1]
	s_waitcnt lgkmcnt(2)
	v_pk_fma_f32 v[66:67], v[66:67], v[42:43], v[58:59]
	v_pk_fma_f32 v[64:65], v[64:65], v[44:45], v[72:73]
	v_pk_fma_f32 v[212:213], v[198:199], v[54:55], v[212:213] op_sel_hi:[0,1,1]
	v_pk_fma_f32 v[250:251], v[198:199], v[56:57], v[250:251] op_sel_hi:[0,1,1]
	v_pk_fma_f32 v[62:63], v[62:63], v[46:47], v[212:213]
	v_pk_fma_f32 v[60:61], v[60:61], v[48:49], v[250:251]
	s_waitcnt lgkmcnt(0)
	v_pk_fma_f32 v[58:59], v[66:67], v[154:155], 0 op_sel_hi:[1,1,0]
	v_pk_fma_f32 v[72:73], v[64:65], v[156:157], 0 op_sel_hi:[1,1,0]
	v_pk_fma_f32 v[58:59], v[62:63], v[246:247], v[58:59]
	v_pk_fma_f32 v[72:73], v[60:61], v[248:249], v[72:73]
	v_add_f32_e32 v207, v58, v59
	v_add_f32_e32 v209, v72, v73
	v_add_f32_e32 v207, v207, v209
	s_nop 1
	v_add_f32_dpp v207, v207, v207 quad_perm:[1,0,3,2] row_mask:0xf bank_mask:0xf bound_ctrl:1
	s_nop 1
	v_add_f32_dpp v207, v207, v207 quad_perm:[2,3,0,1] row_mask:0xf bank_mask:0xf bound_ctrl:1
	s_nop 1
	v_add_f32_dpp v205, v207, v207 row_half_mirror row_mask:0xf bank_mask:0xf bound_ctrl:1
	s_and_saveexec_b64 s[18:19], s[12:13]
	ds_write_b32 v162, v205 offset:1920
	s_mov_b64 exec, s[18:19]

; DI float oct_sum(float v) { v += dpp_f<0xB1>(v); v += dpp_f<0x4E>(v); v += dpp_f<0x141>(v); return v; }
; DI void scan_item(const Params& p, int b, int h, int half, char* smem, unsigned* pgen, unsigned kp) {
;     ...
; #pragma unroll 1
;     for (int sg = 0; sg < SC; sg += 4) {
;       float yy[4];
; #pragma unroll
;       for (int s4 = 0; s4 < 4; ++s4) {
;         const int s = sg + s4;
;         const f32x2* a2 = (const f32x2*)(Al + s * 64 + cg * 8);
;         const f32x2* w2 = (const f32x2*)(Wl + s * 64 + cg * 8);
;         const f32x2* b2 = (const f32x2*)(Bl + s * 64 + cg * 8);
;         const f32x2* k2 = (const f32x2*)(Kl + s * 64 + cg * 8);
;         const f32x2* r2 = (const f32x2*)(Rl + s * 64 + cg * 8);
;         f32x2 o[20];
; #pragma unroll
;         for (int i = 0; i < 4; ++i) { o[i] = a2[i]; o[4 + i] = w2[i]; o[8 + i] = b2[i]; o[12 + i] = k2[i]; o[16 + i] = r2[i]; }
;         const float vr = Vl[s * 64 + 32 * half + rp];
;         f32x2 p0 = St[0] * o[0], p1 = St[1] * o[1];
;         p0 = __builtin_elementwise_fma(St[2], o[2], p0); p1 = __builtin_elementwise_fma(St[3], o[3], p1);
;         const float sa = oct_sum((p0.x + p0.y) + (p1.x + p1.y));
;         const f32x2 sv = {sa, sa}, vv = {vr, vr};
;         f32x2 y0 = {0.f, 0.f}, y1 = {0.f, 0.f};
; #pragma unroll
;         for (int i = 0; i < 4; i += 2) {
;           St[i] = __builtin_elementwise_fma(St[i], o[4 + i], __builtin_elementwise_fma(sv, o[8 + i], vv * o[12 + i]));
;           St[i + 1] = __builtin_elementwise_fma(St[i + 1], o[5 + i], __builtin_elementwise_fma(sv, o[9 + i], vv * o[13 + i]));
;           y0 = __builtin_elementwise_fma(St[i], o[16 + i], y0);
;           y1 = __builtin_elementwise_fma(St[i + 1], o[17 + i], y1);
;         }
;         yy[s4] = oct_sum((y0.x + y0.y) + (y1.x + y1.y));
;       }
;       if (cg == 0) {
; #pragma unroll
;         for (int s4 = 0; s4 < 4; ++s4) Yl[(sg + s4) * 32 + rp] = yy[s4];
;       }
.LBB0_711:
	s_mov_b32 s18, -4
	v_mov_b32_e32 v0, v214
	v_mov_b32_e32 v161, v160
	v_mov_b32_e32 v162, v225
	ds_read_b128 v[34:37], v0 offset:16384
	ds_read_b128 v[38:41], v0 offset:16400
	ds_read_b128 v[68:71], v0 offset:8192
	ds_read_b128 v[150:153], v0 offset:8208
	ds_read2st64_b32 v[158:159], v161 offset0:0 offset1:1
	ds_read_b128 v[50:53], v0 offset:20480
	ds_read_b128 v[54:57], v0 offset:20496
	ds_read_b128 v[42:45], v0 offset:4096
	ds_read_b128 v[46:49], v0 offset:4112
	ds_read_b128 v[154:157], v0 offset:0
	ds_read_b128 v[246:249], v0 offset:16
	ds_read_b128 v[200:203], v0 offset:16640
	ds_read_b128 v[230:233], v0 offset:16656
	s_waitcnt lgkmcnt(11)
	v_pk_mul_f32 v[34:35], v[66:67], v[34:35]
	v_pk_mul_f32 v[36:37], v[64:65], v[36:37]
	v_pk_fma_f32 v[34:35], v[62:63], v[38:39], v[34:35]
	v_pk_fma_f32 v[36:37], v[60:61], v[40:41], v[36:37]
	v_add_f32_e32 v198, v34, v35
	v_add_f32_e32 v199, v36, v37
	v_add_f32_e32 v198, v198, v199
	s_waitcnt lgkmcnt(8)
	v_pk_mul_f32 v[58:59], v[68:69], v[158:159] op_sel_hi:[1,0]
	v_pk_mul_f32 v[72:73], v[70:71], v[158:159] op_sel_hi:[1,0]
	ds_read_b128 v[68:71], v0 offset:8448
	v_add_f32_dpp v198, v198, v198 quad_perm:[1,0,3,2] row_mask:0xf bank_mask:0xf bound_ctrl:1
	s_nop 0
	v_pk_mul_f32 v[212:213], v[150:151], v[158:159] op_sel_hi:[1,0]
	v_add_f32_dpp v198, v198, v198 quad_perm:[2,3,0,1] row_mask:0xf bank_mask:0xf bound_ctrl:1
	s_nop 0
	v_pk_mul_f32 v[250:251], v[152:153], v[158:159] op_sel_hi:[1,0]
	ds_read_b128 v[150:153], v0 offset:8464
	v_add_f32_dpp v198, v198, v198 row_half_mirror row_mask:0xf bank_mask:0xf bound_ctrl:1
	s_waitcnt lgkmcnt(8)
	v_pk_fma_f32 v[58:59], v[198:199], v[50:51], v[58:59] op_sel_hi:[0,1,1]
	v_pk_fma_f32 v[72:73], v[198:199], v[52:53], v[72:73] op_sel_hi:[0,1,1]
	s_waitcnt lgkmcnt(6)
	v_pk_fma_f32 v[66:67], v[66:67], v[42:43], v[58:59]
	v_pk_fma_f32 v[64:65], v[64:65], v[44:45], v[72:73]
	v_pk_fma_f32 v[212:213], v[198:199], v[54:55], v[212:213] op_sel_hi:[0,1,1]
	v_pk_fma_f32 v[250:251], v[198:199], v[56:57], v[250:251] op_sel_hi:[0,1,1]
	v_pk_fma_f32 v[62:63], v[62:63], v[46:47], v[212:213]
	v_pk_fma_f32 v[60:61], v[60:61], v[48:49], v[250:251]
	ds_read_b128 v[50:53], v0 offset:20736
	ds_read_b128 v[54:57], v0 offset:20752
	ds_read_b128 v[42:45], v0 offset:4352
	ds_read_b128 v[46:49], v0 offset:4368
	s_waitcnt lgkmcnt(8)
	v_pk_fma_f32 v[58:59], v[66:67], v[154:155], 0 op_sel_hi:[1,1,0]
	v_pk_fma_f32 v[72:73], v[64:65], v[156:157], 0 op_sel_hi:[1,1,0]
	v_pk_fma_f32 v[58:59], v[62:63], v[246:247], v[58:59]
	v_pk_fma_f32 v[72:73], v[60:61], v[248:249], v[72:73]
	ds_read_b128 v[154:157], v0 offset:256
	ds_read_b128 v[246:249], v0 offset:272
	v_add_f32_e32 v207, v58, v59
	v_add_f32_e32 v209, v72, v73
	ds_read_b128 v[34:37], v0 offset:16896
	ds_read_b128 v[38:41], v0 offset:16912
	s_waitcnt lgkmcnt(10)
	v_pk_mul_f32 v[200:201], v[66:67], v[200:201]
	v_pk_mul_f32 v[202:203], v[64:65], v[202:203]
	v_pk_fma_f32 v[200:201], v[62:63], v[230:231], v[200:201]
	v_pk_fma_f32 v[202:203], v[60:61], v[232:233], v[202:203]
	v_add_f32_e32 v198, v200, v201
	v_add_f32_e32 v199, v202, v203
	v_add_f32_e32 v207, v207, v209
	v_add_f32_e32 v198, v198, v199
	s_waitcnt lgkmcnt(8)
	v_mov_b32_e32 v232, v159
	v_pk_mul_f32 v[58:59], v[68:69], v[232:233] op_sel_hi:[1,0]
	v_pk_mul_f32 v[72:73], v[70:71], v[232:233] op_sel_hi:[1,0]
	ds_read_b128 v[68:71], v0 offset:8704
	v_add_f32_dpp v198, v198, v198 quad_perm:[1,0,3,2] row_mask:0xf bank_mask:0xf bound_ctrl:1
	v_add_f32_dpp v207, v207, v207 quad_perm:[1,0,3,2] row_mask:0xf bank_mask:0xf bound_ctrl:1
	v_pk_mul_f32 v[212:213], v[150:151], v[232:233] op_sel_hi:[1,0]
	v_add_f32_dpp v198, v198, v198 quad_perm:[2,3,0,1] row_mask:0xf bank_mask:0xf bound_ctrl:1
	v_add_f32_dpp v207, v207, v207 quad_perm:[2,3,0,1] row_mask:0xf bank_mask:0xf bound_ctrl:1
	v_pk_mul_f32 v[250:251], v[152:153], v[232:233] op_sel_hi:[1,0]
	ds_read_b128 v[150:153], v0 offset:8720
	v_add_f32_dpp v198, v198, v198 row_half_mirror row_mask:0xf bank_mask:0xf bound_ctrl:1
	v_add_f32_dpp v163, v207, v207 row_half_mirror row_mask:0xf bank_mask:0xf bound_ctrl:1
	ds_read2st64_b32 v[158:159], v161 offset0:2 offset1:3
	s_and_saveexec_b64 s[4:5], s[12:13]
	ds_write_b32 v162, v163 offset:0
	s_mov_b64 exec, s[4:5]
	s_waitcnt lgkmcnt(9)
	v_pk_fma_f32 v[58:59], v[198:199], v[50:51], v[58:59] op_sel_hi:[0,1,1]
	v_pk_fma_f32 v[72:73], v[198:199], v[52:53], v[72:73] op_sel_hi:[0,1,1]
	s_waitcnt lgkmcnt(7)
	v_pk_fma_f32 v[66:67], v[66:67], v[42:43], v[58:59]
	v_pk_fma_f32 v[64:65], v[64:65], v[44:45], v[72:73]
	v_pk_fma_f32 v[212:213], v[198:199], v[54:55], v[212:213] op_sel_hi:[0,1,1]
	v_pk_fma_f32 v[250:251], v[198:199], v[56:57], v[250:251] op_sel_hi:[0,1,1]
	v_pk_fma_f32 v[62:63], v[62:63], v[46:47], v[212:213]
	v_pk_fma_f32 v[60:61], v[60:61], v[48:49], v[250:251]
	ds_read_b128 v[50:53], v0 offset:20992
	ds_read_b128 v[54:57], v0 offset:21008
	ds_read_b128 v[42:45], v0 offset:4608
	ds_read_b128 v[46:49], v0 offset:4624
	s_waitcnt lgkmcnt(9)
	v_pk_fma_f32 v[58:59], v[66:67], v[154:155], 0 op_sel_hi:[1,1,0]
	v_pk_fma_f32 v[72:73], v[64:65], v[156:157], 0 op_sel_hi:[1,1,0]
	v_pk_fma_f32 v[58:59], v[62:63], v[246:247], v[58:59]
	v_pk_fma_f32 v[72:73], v[60:61], v[248:249], v[72:73]
	ds_read_b128 v[154:157], v0 offset:512
	ds_read_b128 v[246:249], v0 offset:528
	v_add_f32_e32 v207, v58, v59
	v_add_f32_e32 v209, v72, v73
	ds_read_b128 v[200:203], v0 offset:17152
	ds_read_b128 v[230:233], v0 offset:17168
	s_waitcnt lgkmcnt(11)
	v_pk_mul_f32 v[34:35], v[66:67], v[34:35]
	v_pk_mul_f32 v[36:37], v[64:65], v[36:37]
	v_pk_fma_f32 v[34:35], v[62:63], v[38:39], v[34:35]
	v_pk_fma_f32 v[36:37], v[60:61], v[40:41], v[36:37]
	v_add_f32_e32 v198, v34, v35
	v_add_f32_e32 v199, v36, v37
	v_add_f32_e32 v207, v207, v209
	v_add_f32_e32 v198, v198, v199
	s_waitcnt lgkmcnt(8)
; DI float oct_sum(float v) { v += dpp_f<0xB1>(v); v += dpp_f<0x4E>(v); v += dpp_f<0x141>(v); return v; }
; DI void scan_item(const Params& p, int b, int h, int half, char* smem, unsigned* pgen, unsigned kp) {
;     ...
; #pragma unroll 1
;     for (int sg = 0; sg < SC; sg += 4) {
;       float yy[4];
; #pragma unroll
;       for (int s4 = 0; s4 < 4; ++s4) {
;         const int s = sg + s4;
;         const f32x2* a2 = (const f32x2*)(Al + s * 64 + cg * 8);
;         const f32x2* w2 = (const f32x2*)(Wl + s * 64 + cg * 8);
;         const f32x2* b2 = (const f32x2*)(Bl + s * 64 + cg * 8);
;         const f32x2* k2 = (const f32x2*)(Kl + s * 64 + cg * 8);
;         const f32x2* r2 = (const f32x2*)(Rl + s * 64 + cg * 8);
;         f32x2 o[20];
; #pragma unroll
;         for (int i = 0; i < 4; ++i) { o[i] = a2[i]; o[4 + i] = w2[i]; o[8 + i] = b2[i]; o[12 + i] = k2[i]; o[16 + i] = r2[i]; }
;         const float vr = Vl[s * 64 + 32 * half + rp];
;         f32x2 p0 = St[0] * o[0], p1 = St[1] * o[1];
;         p0 = __builtin_elementwise_fma(St[2], o[2], p0); p1 = __builtin_elementwise_fma(St[3], o[3], p1);
;         const float sa = oct_sum((p0.x + p0.y) + (p1.x + p1.y));
;         const f32x2 sv = {sa, sa}, vv = {vr, vr};
;         f32x2 y0 = {0.f, 0.f}, y1 = {0.f, 0.f};
; #pragma unroll
;         for (int i = 0; i < 4; i += 2) {
;           St[i] = __builtin_elementwise_fma(St[i], o[4 + i], __builtin_elementwise_fma(sv, o[8 + i], vv * o[12 + i]));
;           St[i + 1] = __builtin_elementwise_fma(St[i + 1], o[5 + i], __builtin_elementwise_fma(sv, o[9 + i], vv * o[13 + i]));
;           y0 = __builtin_elementwise_fma(St[i], o[16 + i], y0);
;           y1 = __builtin_elementwise_fma(St[i + 1], o[17 + i], y1);
;         }
;         yy[s4] = oct_sum((y0.x + y0.y) + (y1.x + y1.y));
;       }
;       if (cg == 0) {
; #pragma unroll
;         for (int s4 = 0; s4 < 4; ++s4) Yl[(sg + s4) * 32 + rp] = yy[s4];
;       }
	v_pk_mul_f32 v[58:59], v[68:69], v[158:159] op_sel_hi:[1,0]
	v_pk_mul_f32 v[72:73], v[70:71], v[158:159] op_sel_hi:[1,0]
	ds_read_b128 v[68:71], v0 offset:8960
	v_add_f32_dpp v198, v198, v198 quad_perm:[1,0,3,2] row_mask:0xf bank_mask:0xf bound_ctrl:1
	v_add_f32_dpp v207, v207, v207 quad_perm:[1,0,3,2] row_mask:0xf bank_mask:0xf bound_ctrl:1
	v_pk_mul_f32 v[212:213], v[150:151], v[158:159] op_sel_hi:[1,0]
	v_add_f32_dpp v198, v198, v198 quad_perm:[2,3,0,1] row_mask:0xf bank_mask:0xf bound_ctrl:1
	v_add_f32_dpp v207, v207, v207 quad_perm:[2,3,0,1] row_mask:0xf bank_mask:0xf bound_ctrl:1
	v_pk_mul_f32 v[250:251], v[152:153], v[158:159] op_sel_hi:[1,0]
	ds_read_b128 v[150:153], v0 offset:8976
	v_add_f32_dpp v198, v198, v198 row_half_mirror row_mask:0xf bank_mask:0xf bound_ctrl:1
	v_add_f32_dpp v205, v207, v207 row_half_mirror row_mask:0xf bank_mask:0xf bound_ctrl:1
	s_and_saveexec_b64 s[4:5], s[12:13]
	ds_write_b32 v162, v205 offset:128
	s_mov_b64 exec, s[4:5]
	s_waitcnt lgkmcnt(8)
	v_pk_fma_f32 v[58:59], v[198:199], v[50:51], v[58:59] op_sel_hi:[0,1,1]
	v_pk_fma_f32 v[72:73], v[198:199], v[52:53], v[72:73] op_sel_hi:[0,1,1]
	s_waitcnt lgkmcnt(6)
	v_pk_fma_f32 v[66:67], v[66:67], v[42:43], v[58:59]
	v_pk_fma_f32 v[64:65], v[64:65], v[44:45], v[72:73]
	v_pk_fma_f32 v[212:213], v[198:199], v[54:55], v[212:213] op_sel_hi:[0,1,1]
	v_pk_fma_f32 v[250:251], v[198:199], v[56:57], v[250:251] op_sel_hi:[0,1,1]
	v_pk_fma_f32 v[62:63], v[62:63], v[46:47], v[212:213]
	v_pk_fma_f32 v[60:61], v[60:61], v[48:49], v[250:251]
	ds_read_b128 v[50:53], v0 offset:21248
	ds_read_b128 v[54:57], v0 offset:21264
	ds_read_b128 v[42:45], v0 offset:4864
	ds_read_b128 v[46:49], v0 offset:4880
	s_waitcnt lgkmcnt(8)
	v_pk_fma_f32 v[58:59], v[66:67], v[154:155], 0 op_sel_hi:[1,1,0]
	v_pk_fma_f32 v[72:73], v[64:65], v[156:157], 0 op_sel_hi:[1,1,0]
	v_pk_fma_f32 v[58:59], v[62:63], v[246:247], v[58:59]
	v_pk_fma_f32 v[72:73], v[60:61], v[248:249], v[72:73]
	ds_read_b128 v[154:157], v0 offset:768
	ds_read_b128 v[246:249], v0 offset:784
	v_add_f32_e32 v207, v58, v59
	v_add_f32_e32 v209, v72, v73
	ds_read_b128 v[34:37], v0 offset:17408
	ds_read_b128 v[38:41], v0 offset:17424
	s_waitcnt lgkmcnt(10)
	v_pk_mul_f32 v[200:201], v[66:67], v[200:201]
	v_pk_mul_f32 v[202:203], v[64:65], v[202:203]
	v_pk_fma_f32 v[200:201], v[62:63], v[230:231], v[200:201]
	v_pk_fma_f32 v[202:203], v[60:61], v[232:233], v[202:203]
	v_add_f32_e32 v198, v200, v201
	v_add_f32_e32 v199, v202, v203
	v_add_f32_e32 v207, v207, v209
	v_add_f32_e32 v198, v198, v199
	s_waitcnt lgkmcnt(8)
	v_mov_b32_e32 v232, v159
	v_pk_mul_f32 v[58:59], v[68:69], v[232:233] op_sel_hi:[1,0]
	v_pk_mul_f32 v[72:73], v[70:71], v[232:233] op_sel_hi:[1,0]
	ds_read_b128 v[68:71], v0 offset:9216
	v_add_f32_dpp v198, v198, v198 quad_perm:[1,0,3,2] row_mask:0xf bank_mask:0xf bound_ctrl:1
	v_add_f32_dpp v207, v207, v207 quad_perm:[1,0,3,2] row_mask:0xf bank_mask:0xf bound_ctrl:1
	v_pk_mul_f32 v[212:213], v[150:151], v[232:233] op_sel_hi:[1,0]
	v_add_f32_dpp v198, v198, v198 quad_perm:[2,3,0,1] row_mask:0xf bank_mask:0xf bound_ctrl:1
	v_add_f32_dpp v207, v207, v207 quad_perm:[2,3,0,1] row_mask:0xf bank_mask:0xf bound_ctrl:1
	v_pk_mul_f32 v[250:251], v[152:153], v[232:233] op_sel_hi:[1,0]
	ds_read_b128 v[150:153], v0 offset:9232
	v_add_f32_dpp v198, v198, v198 row_half_mirror row_mask:0xf bank_mask:0xf bound_ctrl:1
	v_add_f32_dpp v163, v207, v207 row_half_mirror row_mask:0xf bank_mask:0xf bound_ctrl:1
	ds_read2st64_b32 v[158:159], v161 offset0:4 offset1:5
	s_and_saveexec_b64 s[4:5], s[12:13]
	ds_write_b32 v162, v163 offset:256
	s_mov_b64 exec, s[4:5]
	s_waitcnt lgkmcnt(9)
	v_pk_fma_f32 v[58:59], v[198:199], v[50:51], v[58:59] op_sel_hi:[0,1,1]
	v_pk_fma_f32 v[72:73], v[198:199], v[52:53], v[72:73] op_sel_hi:[0,1,1]
	s_waitcnt lgkmcnt(7)
	v_pk_fma_f32 v[66:67], v[66:67], v[42:43], v[58:59]
	v_pk_fma_f32 v[64:65], v[64:65], v[44:45], v[72:73]
	v_pk_fma_f32 v[212:213], v[198:199], v[54:55], v[212:213] op_sel_hi:[0,1,1]
	v_pk_fma_f32 v[250:251], v[198:199], v[56:57], v[250:251] op_sel_hi:[0,1,1]
	v_pk_fma_f32 v[62:63], v[62:63], v[46:47], v[212:213]
	v_pk_fma_f32 v[60:61], v[60:61], v[48:49], v[250:251]
	ds_read_b128 v[50:53], v0 offset:21504
	ds_read_b128 v[54:57], v0 offset:21520
	ds_read_b128 v[42:45], v0 offset:5120
	ds_read_b128 v[46:49], v0 offset:5136
	s_waitcnt lgkmcnt(9)
	v_pk_fma_f32 v[58:59], v[66:67], v[154:155], 0 op_sel_hi:[1,1,0]
	v_pk_fma_f32 v[72:73], v[64:65], v[156:157], 0 op_sel_hi:[1,1,0]
	v_pk_fma_f32 v[58:59], v[62:63], v[246:247], v[58:59]
	v_pk_fma_f32 v[72:73], v[60:61], v[248:249], v[72:73]
	ds_read_b128 v[154:157], v0 offset:1024
	ds_read_b128 v[246:249], v0 offset:1040
	v_add_f32_e32 v207, v58, v59
	v_add_f32_e32 v209, v72, v73
	ds_read_b128 v[200:203], v0 offset:17664
	ds_read_b128 v[230:233], v0 offset:17680
	s_waitcnt lgkmcnt(11)
	v_pk_mul_f32 v[34:35], v[66:67], v[34:35]
	v_pk_mul_f32 v[36:37], v[64:65], v[36:37]
	v_pk_fma_f32 v[34:35], v[62:63], v[38:39], v[34:35]
	v_pk_fma_f32 v[36:37], v[60:61], v[40:41], v[36:37]
	v_add_f32_e32 v198, v34, v35
	v_add_f32_e32 v199, v36, v37
	v_add_f32_e32 v207, v207, v209
	v_add_f32_e32 v198, v198, v199
	s_waitcnt lgkmcnt(8)
; DI float oct_sum(float v) { v += dpp_f<0xB1>(v); v += dpp_f<0x4E>(v); v += dpp_f<0x141>(v); return v; }
; DI void scan_item(const Params& p, int b, int h, int half, char* smem, unsigned* pgen, unsigned kp) {
;     ...
; #pragma unroll 1
;     for (int sg = 0; sg < SC; sg += 4) {
;       float yy[4];
; #pragma unroll
;       for (int s4 = 0; s4 < 4; ++s4) {
;         const int s = sg + s4;
;         const f32x2* a2 = (const f32x2*)(Al + s * 64 + cg * 8);
;         const f32x2* w2 = (const f32x2*)(Wl + s * 64 + cg * 8);
;         const f32x2* b2 = (const f32x2*)(Bl + s * 64 + cg * 8);
;         const f32x2* k2 = (const f32x2*)(Kl + s * 64 + cg * 8);
;         const f32x2* r2 = (const f32x2*)(Rl + s * 64 + cg * 8);
;         f32x2 o[20];
; #pragma unroll
;         for (int i = 0; i < 4; ++i) { o[i] = a2[i]; o[4 + i] = w2[i]; o[8 + i] = b2[i]; o[12 + i] = k2[i]; o[16 + i] = r2[i]; }
;         const float vr = Vl[s * 64 + 32 * half + rp];
;         f32x2 p0 = St[0] * o[0], p1 = St[1] * o[1];
;         p0 = __builtin_elementwise_fma(St[2], o[2], p0); p1 = __builtin_elementwise_fma(St[3], o[3], p1);
;         const float sa = oct_sum((p0.x + p0.y) + (p1.x + p1.y));
;         const f32x2 sv = {sa, sa}, vv = {vr, vr};
;         f32x2 y0 = {0.f, 0.f}, y1 = {0.f, 0.f};
; #pragma unroll
;         for (int i = 0; i < 4; i += 2) {
;           St[i] = __builtin_elementwise_fma(St[i], o[4 + i], __builtin_elementwise_fma(sv, o[8 + i], vv * o[12 + i]));
;           St[i + 1] = __builtin_elementwise_fma(St[i + 1], o[5 + i], __builtin_elementwise_fma(sv, o[9 + i], vv * o[13 + i]));
;           y0 = __builtin_elementwise_fma(St[i], o[16 + i], y0);
;           y1 = __builtin_elementwise_fma(St[i + 1], o[17 + i], y1);
;         }
;         yy[s4] = oct_sum((y0.x + y0.y) + (y1.x + y1.y));
;       }
;       if (cg == 0) {
; #pragma unroll
;         for (int s4 = 0; s4 < 4; ++s4) Yl[(sg + s4) * 32 + rp] = yy[s4];
;       }
	v_pk_mul_f32 v[58:59], v[68:69], v[158:159] op_sel_hi:[1,0]
	v_pk_mul_f32 v[72:73], v[70:71], v[158:159] op_sel_hi:[1,0]
	ds_read_b128 v[68:71], v0 offset:9472
	v_add_f32_dpp v198, v198, v198 quad_perm:[1,0,3,2] row_mask:0xf bank_mask:0xf bound_ctrl:1
	v_add_f32_dpp v207, v207, v207 quad_perm:[1,0,3,2] row_mask:0xf bank_mask:0xf bound_ctrl:1
	v_pk_mul_f32 v[212:213], v[150:151], v[158:159] op_sel_hi:[1,0]
	v_add_f32_dpp v198, v198, v198 quad_perm:[2,3,0,1] row_mask:0xf bank_mask:0xf bound_ctrl:1
	v_add_f32_dpp v207, v207, v207 quad_perm:[2,3,0,1] row_mask:0xf bank_mask:0xf bound_ctrl:1
	v_pk_mul_f32 v[250:251], v[152:153], v[158:159] op_sel_hi:[1,0]
	ds_read_b128 v[150:153], v0 offset:9488
	v_add_f32_dpp v198, v198, v198 row_half_mirror row_mask:0xf bank_mask:0xf bound_ctrl:1
	v_add_f32_dpp v205, v207, v207 row_half_mirror row_mask:0xf bank_mask:0xf bound_ctrl:1
	s_and_saveexec_b64 s[4:5], s[12:13]
	ds_write_b32 v162, v205 offset:384
	s_mov_b64 exec, s[4:5]
	s_waitcnt lgkmcnt(8)
	v_pk_fma_f32 v[58:59], v[198:199], v[50:51], v[58:59] op_sel_hi:[0,1,1]
	v_pk_fma_f32 v[72:73], v[198:199], v[52:53], v[72:73] op_sel_hi:[0,1,1]
	s_waitcnt lgkmcnt(6)
	v_pk_fma_f32 v[66:67], v[66:67], v[42:43], v[58:59]
	v_pk_fma_f32 v[64:65], v[64:65], v[44:45], v[72:73]
	v_pk_fma_f32 v[212:213], v[198:199], v[54:55], v[212:213] op_sel_hi:[0,1,1]
	v_pk_fma_f32 v[250:251], v[198:199], v[56:57], v[250:251] op_sel_hi:[0,1,1]
	v_pk_fma_f32 v[62:63], v[62:63], v[46:47], v[212:213]
	v_pk_fma_f32 v[60:61], v[60:61], v[48:49], v[250:251]
	ds_read_b128 v[50:53], v0 offset:21760
	ds_read_b128 v[54:57], v0 offset:21776
	ds_read_b128 v[42:45], v0 offset:5376
	ds_read_b128 v[46:49], v0 offset:5392
	s_waitcnt lgkmcnt(8)
	v_pk_fma_f32 v[58:59], v[66:67], v[154:155], 0 op_sel_hi:[1,1,0]
	v_pk_fma_f32 v[72:73], v[64:65], v[156:157], 0 op_sel_hi:[1,1,0]
	v_pk_fma_f32 v[58:59], v[62:63], v[246:247], v[58:59]
	v_pk_fma_f32 v[72:73], v[60:61], v[248:249], v[72:73]
	ds_read_b128 v[154:157], v0 offset:1280
	ds_read_b128 v[246:249], v0 offset:1296
	v_add_f32_e32 v207, v58, v59
	v_add_f32_e32 v209, v72, v73
	ds_read_b128 v[34:37], v0 offset:17920
	ds_read_b128 v[38:41], v0 offset:17936
	s_waitcnt lgkmcnt(10)
	v_pk_mul_f32 v[200:201], v[66:67], v[200:201]
	v_pk_mul_f32 v[202:203], v[64:65], v[202:203]
	v_pk_fma_f32 v[200:201], v[62:63], v[230:231], v[200:201]
	v_pk_fma_f32 v[202:203], v[60:61], v[232:233], v[202:203]
	v_add_f32_e32 v198, v200, v201
	v_add_f32_e32 v199, v202, v203
	v_add_f32_e32 v207, v207, v209
	v_add_f32_e32 v198, v198, v199
	s_waitcnt lgkmcnt(8)
	v_mov_b32_e32 v232, v159
	v_pk_mul_f32 v[58:59], v[68:69], v[232:233] op_sel_hi:[1,0]
	v_pk_mul_f32 v[72:73], v[70:71], v[232:233] op_sel_hi:[1,0]
	ds_read_b128 v[68:71], v0 offset:9728
	v_add_f32_dpp v198, v198, v198 quad_perm:[1,0,3,2] row_mask:0xf bank_mask:0xf bound_ctrl:1
	v_add_f32_dpp v207, v207, v207 quad_perm:[1,0,3,2] row_mask:0xf bank_mask:0xf bound_ctrl:1
	v_pk_mul_f32 v[212:213], v[150:151], v[232:233] op_sel_hi:[1,0]
	v_add_f32_dpp v198, v198, v198 quad_perm:[2,3,0,1] row_mask:0xf bank_mask:0xf bound_ctrl:1
	v_add_f32_dpp v207, v207, v207 quad_perm:[2,3,0,1] row_mask:0xf bank_mask:0xf bound_ctrl:1
	v_pk_mul_f32 v[250:251], v[152:153], v[232:233] op_sel_hi:[1,0]
	ds_read_b128 v[150:153], v0 offset:9744
	v_add_f32_dpp v198, v198, v198 row_half_mirror row_mask:0xf bank_mask:0xf bound_ctrl:1
	v_add_f32_dpp v163, v207, v207 row_half_mirror row_mask:0xf bank_mask:0xf bound_ctrl:1
	ds_read2st64_b32 v[158:159], v161 offset0:6 offset1:7
	s_and_saveexec_b64 s[4:5], s[12:13]
	ds_write_b32 v162, v163 offset:512
	s_mov_b64 exec, s[4:5]
	s_waitcnt lgkmcnt(9)
	v_pk_fma_f32 v[58:59], v[198:199], v[50:51], v[58:59] op_sel_hi:[0,1,1]
	v_pk_fma_f32 v[72:73], v[198:199], v[52:53], v[72:73] op_sel_hi:[0,1,1]
	s_waitcnt lgkmcnt(7)
	v_pk_fma_f32 v[66:67], v[66:67], v[42:43], v[58:59]
	v_pk_fma_f32 v[64:65], v[64:65], v[44:45], v[72:73]
	v_pk_fma_f32 v[212:213], v[198:199], v[54:55], v[212:213] op_sel_hi:[0,1,1]
	v_pk_fma_f32 v[250:251], v[198:199], v[56:57], v[250:251] op_sel_hi:[0,1,1]
	v_pk_fma_f32 v[62:63], v[62:63], v[46:47], v[212:213]
	v_pk_fma_f32 v[60:61], v[60:61], v[48:49], v[250:251]
	ds_read_b128 v[50:53], v0 offset:22016
	ds_read_b128 v[54:57], v0 offset:22032
	ds_read_b128 v[42:45], v0 offset:5632
	ds_read_b128 v[46:49], v0 offset:5648
	s_waitcnt lgkmcnt(9)
	v_pk_fma_f32 v[58:59], v[66:67], v[154:155], 0 op_sel_hi:[1,1,0]
	v_pk_fma_f32 v[72:73], v[64:65], v[156:157], 0 op_sel_hi:[1,1,0]
	v_pk_fma_f32 v[58:59], v[62:63], v[246:247], v[58:59]
	v_pk_fma_f32 v[72:73], v[60:61], v[248:249], v[72:73]
	ds_read_b128 v[154:157], v0 offset:1536
	ds_read_b128 v[246:249], v0 offset:1552
	v_add_f32_e32 v207, v58, v59
	v_add_f32_e32 v209, v72, v73
	ds_read_b128 v[200:203], v0 offset:18176
	ds_read_b128 v[230:233], v0 offset:18192
	s_waitcnt lgkmcnt(11)
	v_pk_mul_f32 v[34:35], v[66:67], v[34:35]
	v_pk_mul_f32 v[36:37], v[64:65], v[36:37]
	v_pk_fma_f32 v[34:35], v[62:63], v[38:39], v[34:35]
	v_pk_fma_f32 v[36:37], v[60:61], v[40:41], v[36:37]
	v_add_f32_e32 v198, v34, v35
	v_add_f32_e32 v199, v36, v37
	v_add_f32_e32 v207, v207, v209
	v_add_f32_e32 v198, v198, v199
	s_waitcnt lgkmcnt(8)
; DI float oct_sum(float v) { v += dpp_f<0xB1>(v); v += dpp_f<0x4E>(v); v += dpp_f<0x141>(v); return v; }
; DI void scan_item(const Params& p, int b, int h, int half, char* smem, unsigned* pgen, unsigned kp) {
;     ...
; #pragma unroll 1
;     for (int sg = 0; sg < SC; sg += 4) {
;       float yy[4];
; #pragma unroll
;       for (int s4 = 0; s4 < 4; ++s4) {
;         const int s = sg + s4;
;         const f32x2* a2 = (const f32x2*)(Al + s * 64 + cg * 8);
;         const f32x2* w2 = (const f32x2*)(Wl + s * 64 + cg * 8);
;         const f32x2* b2 = (const f32x2*)(Bl + s * 64 + cg * 8);
;         const f32x2* k2 = (const f32x2*)(Kl + s * 64 + cg * 8);
;         const f32x2* r2 = (const f32x2*)(Rl + s * 64 + cg * 8);
;         f32x2 o[20];
; #pragma unroll
;         for (int i = 0; i < 4; ++i) { o[i] = a2[i]; o[4 + i] = w2[i]; o[8 + i] = b2[i]; o[12 + i] = k2[i]; o[16 + i] = r2[i]; }
;         const float vr = Vl[s * 64 + 32 * half + rp];
;         f32x2 p0 = St[0] * o[0], p1 = St[1] * o[1];
;         p0 = __builtin_elementwise_fma(St[2], o[2], p0); p1 = __builtin_elementwise_fma(St[3], o[3], p1);
;         const float sa = oct_sum((p0.x + p0.y) + (p1.x + p1.y));
;         const f32x2 sv = {sa, sa}, vv = {vr, vr};
;         f32x2 y0 = {0.f, 0.f}, y1 = {0.f, 0.f};
; #pragma unroll
;         for (int i = 0; i < 4; i += 2) {
;           St[i] = __builtin_elementwise_fma(St[i], o[4 + i], __builtin_elementwise_fma(sv, o[8 + i], vv * o[12 + i]));
;           St[i + 1] = __builtin_elementwise_fma(St[i + 1], o[5 + i], __builtin_elementwise_fma(sv, o[9 + i], vv * o[13 + i]));
;           y0 = __builtin_elementwise_fma(St[i], o[16 + i], y0);
;           y1 = __builtin_elementwise_fma(St[i + 1], o[17 + i], y1);
;         }
;         yy[s4] = oct_sum((y0.x + y0.y) + (y1.x + y1.y));
;       }
;       if (cg == 0) {
; #pragma unroll
;         for (int s4 = 0; s4 < 4; ++s4) Yl[(sg + s4) * 32 + rp] = yy[s4];
;       }
	v_pk_mul_f32 v[58:59], v[68:69], v[158:159] op_sel_hi:[1,0]
	v_pk_mul_f32 v[72:73], v[70:71], v[158:159] op_sel_hi:[1,0]
	ds_read_b128 v[68:71], v0 offset:9984
	v_add_f32_dpp v198, v198, v198 quad_perm:[1,0,3,2] row_mask:0xf bank_mask:0xf bound_ctrl:1
	v_add_f32_dpp v207, v207, v207 quad_perm:[1,0,3,2] row_mask:0xf bank_mask:0xf bound_ctrl:1
	v_pk_mul_f32 v[212:213], v[150:151], v[158:159] op_sel_hi:[1,0]
	v_add_f32_dpp v198, v198, v198 quad_perm:[2,3,0,1] row_mask:0xf bank_mask:0xf bound_ctrl:1
	v_add_f32_dpp v207, v207, v207 quad_perm:[2,3,0,1] row_mask:0xf bank_mask:0xf bound_ctrl:1
	v_pk_mul_f32 v[250:251], v[152:153], v[158:159] op_sel_hi:[1,0]
	ds_read_b128 v[150:153], v0 offset:10000
	v_add_f32_dpp v198, v198, v198 row_half_mirror row_mask:0xf bank_mask:0xf bound_ctrl:1
	v_add_f32_dpp v205, v207, v207 row_half_mirror row_mask:0xf bank_mask:0xf bound_ctrl:1
	s_and_saveexec_b64 s[4:5], s[12:13]
	ds_write_b32 v162, v205 offset:640
	s_mov_b64 exec, s[4:5]
	s_waitcnt lgkmcnt(8)
	v_pk_fma_f32 v[58:59], v[198:199], v[50:51], v[58:59] op_sel_hi:[0,1,1]
	v_pk_fma_f32 v[72:73], v[198:199], v[52:53], v[72:73] op_sel_hi:[0,1,1]
	s_waitcnt lgkmcnt(6)
	v_pk_fma_f32 v[66:67], v[66:67], v[42:43], v[58:59]
	v_pk_fma_f32 v[64:65], v[64:65], v[44:45], v[72:73]
	v_pk_fma_f32 v[212:213], v[198:199], v[54:55], v[212:213] op_sel_hi:[0,1,1]
	v_pk_fma_f32 v[250:251], v[198:199], v[56:57], v[250:251] op_sel_hi:[0,1,1]
	v_pk_fma_f32 v[62:63], v[62:63], v[46:47], v[212:213]
	v_pk_fma_f32 v[60:61], v[60:61], v[48:49], v[250:251]
	ds_read_b128 v[50:53], v0 offset:22272
	ds_read_b128 v[54:57], v0 offset:22288
	ds_read_b128 v[42:45], v0 offset:5888
	ds_read_b128 v[46:49], v0 offset:5904
	s_waitcnt lgkmcnt(8)
	v_pk_fma_f32 v[58:59], v[66:67], v[154:155], 0 op_sel_hi:[1,1,0]
	v_pk_fma_f32 v[72:73], v[64:65], v[156:157], 0 op_sel_hi:[1,1,0]
	v_pk_fma_f32 v[58:59], v[62:63], v[246:247], v[58:59]
	v_pk_fma_f32 v[72:73], v[60:61], v[248:249], v[72:73]
	ds_read_b128 v[154:157], v0 offset:1792
	ds_read_b128 v[246:249], v0 offset:1808
	v_add_f32_e32 v207, v58, v59
	v_add_f32_e32 v209, v72, v73
	ds_read_b128 v[34:37], v0 offset:18432
	ds_read_b128 v[38:41], v0 offset:18448
	s_waitcnt lgkmcnt(10)
	v_pk_mul_f32 v[200:201], v[66:67], v[200:201]
	v_pk_mul_f32 v[202:203], v[64:65], v[202:203]
	v_pk_fma_f32 v[200:201], v[62:63], v[230:231], v[200:201]
	v_pk_fma_f32 v[202:203], v[60:61], v[232:233], v[202:203]
	v_add_f32_e32 v198, v200, v201
	v_add_f32_e32 v199, v202, v203
	v_add_f32_e32 v207, v207, v209
	v_add_f32_e32 v198, v198, v199
	s_waitcnt lgkmcnt(8)
	v_mov_b32_e32 v232, v159
	v_pk_mul_f32 v[58:59], v[68:69], v[232:233] op_sel_hi:[1,0]
	v_pk_mul_f32 v[72:73], v[70:71], v[232:233] op_sel_hi:[1,0]
	ds_read_b128 v[68:71], v0 offset:10240
	v_add_f32_dpp v198, v198, v198 quad_perm:[1,0,3,2] row_mask:0xf bank_mask:0xf bound_ctrl:1
	v_add_f32_dpp v207, v207, v207 quad_perm:[1,0,3,2] row_mask:0xf bank_mask:0xf bound_ctrl:1
	v_pk_mul_f32 v[212:213], v[150:151], v[232:233] op_sel_hi:[1,0]
	v_add_f32_dpp v198, v198, v198 quad_perm:[2,3,0,1] row_mask:0xf bank_mask:0xf bound_ctrl:1
	v_add_f32_dpp v207, v207, v207 quad_perm:[2,3,0,1] row_mask:0xf bank_mask:0xf bound_ctrl:1
	v_pk_mul_f32 v[250:251], v[152:153], v[232:233] op_sel_hi:[1,0]
	ds_read_b128 v[150:153], v0 offset:10256
	v_add_f32_dpp v198, v198, v198 row_half_mirror row_mask:0xf bank_mask:0xf bound_ctrl:1
	v_add_f32_dpp v163, v207, v207 row_half_mirror row_mask:0xf bank_mask:0xf bound_ctrl:1
	ds_read2st64_b32 v[158:159], v161 offset0:8 offset1:9
	s_and_saveexec_b64 s[4:5], s[12:13]
	ds_write_b32 v162, v163 offset:768
	s_mov_b64 exec, s[4:5]
	s_waitcnt lgkmcnt(9)
	v_pk_fma_f32 v[58:59], v[198:199], v[50:51], v[58:59] op_sel_hi:[0,1,1]
	v_pk_fma_f32 v[72:73], v[198:199], v[52:53], v[72:73] op_sel_hi:[0,1,1]
	s_waitcnt lgkmcnt(7)
	v_pk_fma_f32 v[66:67], v[66:67], v[42:43], v[58:59]
	v_pk_fma_f32 v[64:65], v[64:65], v[44:45], v[72:73]
	v_pk_fma_f32 v[212:213], v[198:199], v[54:55], v[212:213] op_sel_hi:[0,1,1]
	v_pk_fma_f32 v[250:251], v[198:199], v[56:57], v[250:251] op_sel_hi:[0,1,1]
	v_pk_fma_f32 v[62:63], v[62:63], v[46:47], v[212:213]
	v_pk_fma_f32 v[60:61], v[60:61], v[48:49], v[250:251]
	ds_read_b128 v[50:53], v0 offset:22528
	ds_read_b128 v[54:57], v0 offset:22544
	ds_read_b128 v[42:45], v0 offset:6144
	ds_read_b128 v[46:49], v0 offset:6160
	s_waitcnt lgkmcnt(9)
	v_pk_fma_f32 v[58:59], v[66:67], v[154:155], 0 op_sel_hi:[1,1,0]
	v_pk_fma_f32 v[72:73], v[64:65], v[156:157], 0 op_sel_hi:[1,1,0]
	v_pk_fma_f32 v[58:59], v[62:63], v[246:247], v[58:59]
	v_pk_fma_f32 v[72:73], v[60:61], v[248:249], v[72:73]
	ds_read_b128 v[154:157], v0 offset:2048
	ds_read_b128 v[246:249], v0 offset:2064
	v_add_f32_e32 v207, v58, v59
	v_add_f32_e32 v209, v72, v73
	ds_read_b128 v[200:203], v0 offset:18688
	ds_read_b128 v[230:233], v0 offset:18704
	s_waitcnt lgkmcnt(11)
	v_pk_mul_f32 v[34:35], v[66:67], v[34:35]
	v_pk_mul_f32 v[36:37], v[64:65], v[36:37]
	v_pk_fma_f32 v[34:35], v[62:63], v[38:39], v[34:35]
	v_pk_fma_f32 v[36:37], v[60:61], v[40:41], v[36:37]
	v_add_f32_e32 v198, v34, v35
	v_add_f32_e32 v199, v36, v37
	v_add_f32_e32 v207, v207, v209
	v_add_f32_e32 v198, v198, v199
	s_waitcnt lgkmcnt(8)
; DI float oct_sum(float v) { v += dpp_f<0xB1>(v); v += dpp_f<0x4E>(v); v += dpp_f<0x141>(v); return v; }
; DI void scan_item(const Params& p, int b, int h, int half, char* smem, unsigned* pgen, unsigned kp) {
;     ...
; #pragma unroll 1
;     for (int sg = 0; sg < SC; sg += 4) {
;       float yy[4];
; #pragma unroll
;       for (int s4 = 0; s4 < 4; ++s4) {
;         const int s = sg + s4;
;         const f32x2* a2 = (const f32x2*)(Al + s * 64 + cg * 8);
;         const f32x2* w2 = (const f32x2*)(Wl + s * 64 + cg * 8);
;         const f32x2* b2 = (const f32x2*)(Bl + s * 64 + cg * 8);
;         const f32x2* k2 = (const f32x2*)(Kl + s * 64 + cg * 8);
;         const f32x2* r2 = (const f32x2*)(Rl + s * 64 + cg * 8);
;         f32x2 o[20];
; #pragma unroll
;         for (int i = 0; i < 4; ++i) { o[i] = a2[i]; o[4 + i] = w2[i]; o[8 + i] = b2[i]; o[12 + i] = k2[i]; o[16 + i] = r2[i]; }
;         const float vr = Vl[s * 64 + 32 * half + rp];
;         f32x2 p0 = St[0] * o[0], p1 = St[1] * o[1];
;         p0 = __builtin_elementwise_fma(St[2], o[2], p0); p1 = __builtin_elementwise_fma(St[3], o[3], p1);
;         const float sa = oct_sum((p0.x + p0.y) + (p1.x + p1.y));
;         const f32x2 sv = {sa, sa}, vv = {vr, vr};
;         f32x2 y0 = {0.f, 0.f}, y1 = {0.f, 0.f};
; #pragma unroll
;         for (int i = 0; i < 4; i += 2) {
;           St[i] = __builtin_elementwise_fma(St[i], o[4 + i], __builtin_elementwise_fma(sv, o[8 + i], vv * o[12 + i]));
;           St[i + 1] = __builtin_elementwise_fma(St[i + 1], o[5 + i], __builtin_elementwise_fma(sv, o[9 + i], vv * o[13 + i]));
;           y0 = __builtin_elementwise_fma(St[i], o[16 + i], y0);
;           y1 = __builtin_elementwise_fma(St[i + 1], o[17 + i], y1);
;         }
;         yy[s4] = oct_sum((y0.x + y0.y) + (y1.x + y1.y));
;       }
;       if (cg == 0) {
; #pragma unroll
;         for (int s4 = 0; s4 < 4; ++s4) Yl[(sg + s4) * 32 + rp] = yy[s4];
;       }
	v_pk_mul_f32 v[58:59], v[68:69], v[158:159] op_sel_hi:[1,0]
	v_pk_mul_f32 v[72:73], v[70:71], v[158:159] op_sel_hi:[1,0]
	ds_read_b128 v[68:71], v0 offset:10496
	v_add_f32_dpp v198, v198, v198 quad_perm:[1,0,3,2] row_mask:0xf bank_mask:0xf bound_ctrl:1
	v_add_f32_dpp v207, v207, v207 quad_perm:[1,0,3,2] row_mask:0xf bank_mask:0xf bound_ctrl:1
	v_pk_mul_f32 v[212:213], v[150:151], v[158:159] op_sel_hi:[1,0]
	v_add_f32_dpp v198, v198, v198 quad_perm:[2,3,0,1] row_mask:0xf bank_mask:0xf bound_ctrl:1
	v_add_f32_dpp v207, v207, v207 quad_perm:[2,3,0,1] row_mask:0xf bank_mask:0xf bound_ctrl:1
	v_pk_mul_f32 v[250:251], v[152:153], v[158:159] op_sel_hi:[1,0]
	ds_read_b128 v[150:153], v0 offset:10512
	v_add_f32_dpp v198, v198, v198 row_half_mirror row_mask:0xf bank_mask:0xf bound_ctrl:1
	v_add_f32_dpp v205, v207, v207 row_half_mirror row_mask:0xf bank_mask:0xf bound_ctrl:1
	s_and_saveexec_b64 s[4:5], s[12:13]
	ds_write_b32 v162, v205 offset:896
	s_mov_b64 exec, s[4:5]
	s_waitcnt lgkmcnt(8)
	v_pk_fma_f32 v[58:59], v[198:199], v[50:51], v[58:59] op_sel_hi:[0,1,1]
	v_pk_fma_f32 v[72:73], v[198:199], v[52:53], v[72:73] op_sel_hi:[0,1,1]
	s_waitcnt lgkmcnt(6)
	v_pk_fma_f32 v[66:67], v[66:67], v[42:43], v[58:59]
	v_pk_fma_f32 v[64:65], v[64:65], v[44:45], v[72:73]
	v_pk_fma_f32 v[212:213], v[198:199], v[54:55], v[212:213] op_sel_hi:[0,1,1]
	v_pk_fma_f32 v[250:251], v[198:199], v[56:57], v[250:251] op_sel_hi:[0,1,1]
	v_pk_fma_f32 v[62:63], v[62:63], v[46:47], v[212:213]
	v_pk_fma_f32 v[60:61], v[60:61], v[48:49], v[250:251]
	ds_read_b128 v[50:53], v0 offset:22784
	ds_read_b128 v[54:57], v0 offset:22800
	ds_read_b128 v[42:45], v0 offset:6400
	ds_read_b128 v[46:49], v0 offset:6416
	s_waitcnt lgkmcnt(8)
	v_pk_fma_f32 v[58:59], v[66:67], v[154:155], 0 op_sel_hi:[1,1,0]
	v_pk_fma_f32 v[72:73], v[64:65], v[156:157], 0 op_sel_hi:[1,1,0]
	v_pk_fma_f32 v[58:59], v[62:63], v[246:247], v[58:59]
	v_pk_fma_f32 v[72:73], v[60:61], v[248:249], v[72:73]
	ds_read_b128 v[154:157], v0 offset:2304
	ds_read_b128 v[246:249], v0 offset:2320
	v_add_f32_e32 v207, v58, v59
	v_add_f32_e32 v209, v72, v73
	ds_read_b128 v[34:37], v0 offset:18944
	ds_read_b128 v[38:41], v0 offset:18960
	s_waitcnt lgkmcnt(10)
	v_pk_mul_f32 v[200:201], v[66:67], v[200:201]
	v_pk_mul_f32 v[202:203], v[64:65], v[202:203]
	v_pk_fma_f32 v[200:201], v[62:63], v[230:231], v[200:201]
	v_pk_fma_f32 v[202:203], v[60:61], v[232:233], v[202:203]
	v_add_f32_e32 v198, v200, v201
	v_add_f32_e32 v199, v202, v203
	v_add_f32_e32 v207, v207, v209
	v_add_f32_e32 v198, v198, v199
	s_waitcnt lgkmcnt(8)
	v_mov_b32_e32 v232, v159
	v_pk_mul_f32 v[58:59], v[68:69], v[232:233] op_sel_hi:[1,0]
	v_pk_mul_f32 v[72:73], v[70:71], v[232:233] op_sel_hi:[1,0]
	ds_read_b128 v[68:71], v0 offset:10752
	v_add_f32_dpp v198, v198, v198 quad_perm:[1,0,3,2] row_mask:0xf bank_mask:0xf bound_ctrl:1
	v_add_f32_dpp v207, v207, v207 quad_perm:[1,0,3,2] row_mask:0xf bank_mask:0xf bound_ctrl:1
	v_pk_mul_f32 v[212:213], v[150:151], v[232:233] op_sel_hi:[1,0]
	v_add_f32_dpp v198, v198, v198 quad_perm:[2,3,0,1] row_mask:0xf bank_mask:0xf bound_ctrl:1
	v_add_f32_dpp v207, v207, v207 quad_perm:[2,3,0,1] row_mask:0xf bank_mask:0xf bound_ctrl:1
	v_pk_mul_f32 v[250:251], v[152:153], v[232:233] op_sel_hi:[1,0]
	ds_read_b128 v[150:153], v0 offset:10768
	v_add_f32_dpp v198, v198, v198 row_half_mirror row_mask:0xf bank_mask:0xf bound_ctrl:1
	v_add_f32_dpp v163, v207, v207 row_half_mirror row_mask:0xf bank_mask:0xf bound_ctrl:1
	ds_read2st64_b32 v[158:159], v161 offset0:10 offset1:11
	s_and_saveexec_b64 s[4:5], s[12:13]
	ds_write_b32 v162, v163 offset:1024
	s_mov_b64 exec, s[4:5]
	s_waitcnt lgkmcnt(9)
	v_pk_fma_f32 v[58:59], v[198:199], v[50:51], v[58:59] op_sel_hi:[0,1,1]
	v_pk_fma_f32 v[72:73], v[198:199], v[52:53], v[72:73] op_sel_hi:[0,1,1]
	s_waitcnt lgkmcnt(7)
	v_pk_fma_f32 v[66:67], v[66:67], v[42:43], v[58:59]
	v_pk_fma_f32 v[64:65], v[64:65], v[44:45], v[72:73]
	v_pk_fma_f32 v[212:213], v[198:199], v[54:55], v[212:213] op_sel_hi:[0,1,1]
	v_pk_fma_f32 v[250:251], v[198:199], v[56:57], v[250:251] op_sel_hi:[0,1,1]
	v_pk_fma_f32 v[62:63], v[62:63], v[46:47], v[212:213]
	v_pk_fma_f32 v[60:61], v[60:61], v[48:49], v[250:251]
	ds_read_b128 v[50:53], v0 offset:23040
	ds_read_b128 v[54:57], v0 offset:23056
	ds_read_b128 v[42:45], v0 offset:6656
	ds_read_b128 v[46:49], v0 offset:6672
	s_waitcnt lgkmcnt(9)
	v_pk_fma_f32 v[58:59], v[66:67], v[154:155], 0 op_sel_hi:[1,1,0]
	v_pk_fma_f32 v[72:73], v[64:65], v[156:157], 0 op_sel_hi:[1,1,0]
	v_pk_fma_f32 v[58:59], v[62:63], v[246:247], v[58:59]
	v_pk_fma_f32 v[72:73], v[60:61], v[248:249], v[72:73]
	ds_read_b128 v[154:157], v0 offset:2560
	ds_read_b128 v[246:249], v0 offset:2576
	v_add_f32_e32 v207, v58, v59
	v_add_f32_e32 v209, v72, v73
	ds_read_b128 v[200:203], v0 offset:19200
	ds_read_b128 v[230:233], v0 offset:19216
	s_waitcnt lgkmcnt(11)
	v_pk_mul_f32 v[34:35], v[66:67], v[34:35]
	v_pk_mul_f32 v[36:37], v[64:65], v[36:37]
	v_pk_fma_f32 v[34:35], v[62:63], v[38:39], v[34:35]
	v_pk_fma_f32 v[36:37], v[60:61], v[40:41], v[36:37]
	v_add_f32_e32 v198, v34, v35
	v_add_f32_e32 v199, v36, v37
	v_add_f32_e32 v207, v207, v209
	v_add_f32_e32 v198, v198, v199
	s_waitcnt lgkmcnt(8)
; DI float oct_sum(float v) { v += dpp_f<0xB1>(v); v += dpp_f<0x4E>(v); v += dpp_f<0x141>(v); return v; }
; DI void scan_item(const Params& p, int b, int h, int half, char* smem, unsigned* pgen, unsigned kp) {
;     ...
; #pragma unroll 1
;     for (int sg = 0; sg < SC; sg += 4) {
;       float yy[4];
; #pragma unroll
;       for (int s4 = 0; s4 < 4; ++s4) {
;         const int s = sg + s4;
;         const f32x2* a2 = (const f32x2*)(Al + s * 64 + cg * 8);
;         const f32x2* w2 = (const f32x2*)(Wl + s * 64 + cg * 8);
;         const f32x2* b2 = (const f32x2*)(Bl + s * 64 + cg * 8);
;         const f32x2* k2 = (const f32x2*)(Kl + s * 64 + cg * 8);
;         const f32x2* r2 = (const f32x2*)(Rl + s * 64 + cg * 8);
;         f32x2 o[20];
; #pragma unroll
;         for (int i = 0; i < 4; ++i) { o[i] = a2[i]; o[4 + i] = w2[i]; o[8 + i] = b2[i]; o[12 + i] = k2[i]; o[16 + i] = r2[i]; }
;         const float vr = Vl[s * 64 + 32 * half + rp];
;         f32x2 p0 = St[0] * o[0], p1 = St[1] * o[1];
;         p0 = __builtin_elementwise_fma(St[2], o[2], p0); p1 = __builtin_elementwise_fma(St[3], o[3], p1);
;         const float sa = oct_sum((p0.x + p0.y) + (p1.x + p1.y));
;         const f32x2 sv = {sa, sa}, vv = {vr, vr};
;         f32x2 y0 = {0.f, 0.f}, y1 = {0.f, 0.f};
; #pragma unroll
;         for (int i = 0; i < 4; i += 2) {
;           St[i] = __builtin_elementwise_fma(St[i], o[4 + i], __builtin_elementwise_fma(sv, o[8 + i], vv * o[12 + i]));
;           St[i + 1] = __builtin_elementwise_fma(St[i + 1], o[5 + i], __builtin_elementwise_fma(sv, o[9 + i], vv * o[13 + i]));
;           y0 = __builtin_elementwise_fma(St[i], o[16 + i], y0);
;           y1 = __builtin_elementwise_fma(St[i + 1], o[17 + i], y1);
;         }
;         yy[s4] = oct_sum((y0.x + y0.y) + (y1.x + y1.y));
;       }
;       if (cg == 0) {
; #pragma unroll
;         for (int s4 = 0; s4 < 4; ++s4) Yl[(sg + s4) * 32 + rp] = yy[s4];
;       }
	v_pk_mul_f32 v[58:59], v[68:69], v[158:159] op_sel_hi:[1,0]
	v_pk_mul_f32 v[72:73], v[70:71], v[158:159] op_sel_hi:[1,0]
	ds_read_b128 v[68:71], v0 offset:11008
	v_add_f32_dpp v198, v198, v198 quad_perm:[1,0,3,2] row_mask:0xf bank_mask:0xf bound_ctrl:1
	v_add_f32_dpp v207, v207, v207 quad_perm:[1,0,3,2] row_mask:0xf bank_mask:0xf bound_ctrl:1
	v_pk_mul_f32 v[212:213], v[150:151], v[158:159] op_sel_hi:[1,0]
	v_add_f32_dpp v198, v198, v198 quad_perm:[2,3,0,1] row_mask:0xf bank_mask:0xf bound_ctrl:1
	v_add_f32_dpp v207, v207, v207 quad_perm:[2,3,0,1] row_mask:0xf bank_mask:0xf bound_ctrl:1
	v_pk_mul_f32 v[250:251], v[152:153], v[158:159] op_sel_hi:[1,0]
	ds_read_b128 v[150:153], v0 offset:11024
	v_add_f32_dpp v198, v198, v198 row_half_mirror row_mask:0xf bank_mask:0xf bound_ctrl:1
	v_add_f32_dpp v205, v207, v207 row_half_mirror row_mask:0xf bank_mask:0xf bound_ctrl:1
	s_and_saveexec_b64 s[4:5], s[12:13]
	ds_write_b32 v162, v205 offset:1152
	s_mov_b64 exec, s[4:5]
	s_waitcnt lgkmcnt(8)
	v_pk_fma_f32 v[58:59], v[198:199], v[50:51], v[58:59] op_sel_hi:[0,1,1]
	v_pk_fma_f32 v[72:73], v[198:199], v[52:53], v[72:73] op_sel_hi:[0,1,1]
	s_waitcnt lgkmcnt(6)
	v_pk_fma_f32 v[66:67], v[66:67], v[42:43], v[58:59]
	v_pk_fma_f32 v[64:65], v[64:65], v[44:45], v[72:73]
	v_pk_fma_f32 v[212:213], v[198:199], v[54:55], v[212:213] op_sel_hi:[0,1,1]
	v_pk_fma_f32 v[250:251], v[198:199], v[56:57], v[250:251] op_sel_hi:[0,1,1]
	v_pk_fma_f32 v[62:63], v[62:63], v[46:47], v[212:213]
	v_pk_fma_f32 v[60:61], v[60:61], v[48:49], v[250:251]
	ds_read_b128 v[50:53], v0 offset:23296
	ds_read_b128 v[54:57], v0 offset:23312
	ds_read_b128 v[42:45], v0 offset:6912
	ds_read_b128 v[46:49], v0 offset:6928
	s_waitcnt lgkmcnt(8)
	v_pk_fma_f32 v[58:59], v[66:67], v[154:155], 0 op_sel_hi:[1,1,0]
	v_pk_fma_f32 v[72:73], v[64:65], v[156:157], 0 op_sel_hi:[1,1,0]
	v_pk_fma_f32 v[58:59], v[62:63], v[246:247], v[58:59]
	v_pk_fma_f32 v[72:73], v[60:61], v[248:249], v[72:73]
	ds_read_b128 v[154:157], v0 offset:2816
	ds_read_b128 v[246:249], v0 offset:2832
	v_add_f32_e32 v207, v58, v59
	v_add_f32_e32 v209, v72, v73
	ds_read_b128 v[34:37], v0 offset:19456
	ds_read_b128 v[38:41], v0 offset:19472
	s_waitcnt lgkmcnt(10)
	v_pk_mul_f32 v[200:201], v[66:67], v[200:201]
	v_pk_mul_f32 v[202:203], v[64:65], v[202:203]
	v_pk_fma_f32 v[200:201], v[62:63], v[230:231], v[200:201]
	v_pk_fma_f32 v[202:203], v[60:61], v[232:233], v[202:203]
	v_add_f32_e32 v198, v200, v201
	v_add_f32_e32 v199, v202, v203
	v_add_f32_e32 v207, v207, v209
	v_add_f32_e32 v198, v198, v199
	s_waitcnt lgkmcnt(8)
	v_mov_b32_e32 v232, v159
	v_pk_mul_f32 v[58:59], v[68:69], v[232:233] op_sel_hi:[1,0]
	v_pk_mul_f32 v[72:73], v[70:71], v[232:233] op_sel_hi:[1,0]
	ds_read_b128 v[68:71], v0 offset:11264
	v_add_f32_dpp v198, v198, v198 quad_perm:[1,0,3,2] row_mask:0xf bank_mask:0xf bound_ctrl:1
	v_add_f32_dpp v207, v207, v207 quad_perm:[1,0,3,2] row_mask:0xf bank_mask:0xf bound_ctrl:1
	v_pk_mul_f32 v[212:213], v[150:151], v[232:233] op_sel_hi:[1,0]
	v_add_f32_dpp v198, v198, v198 quad_perm:[2,3,0,1] row_mask:0xf bank_mask:0xf bound_ctrl:1
	v_add_f32_dpp v207, v207, v207 quad_perm:[2,3,0,1] row_mask:0xf bank_mask:0xf bound_ctrl:1
	v_pk_mul_f32 v[250:251], v[152:153], v[232:233] op_sel_hi:[1,0]
	ds_read_b128 v[150:153], v0 offset:11280
	v_add_f32_dpp v198, v198, v198 row_half_mirror row_mask:0xf bank_mask:0xf bound_ctrl:1
	v_add_f32_dpp v163, v207, v207 row_half_mirror row_mask:0xf bank_mask:0xf bound_ctrl:1
	ds_read2st64_b32 v[158:159], v161 offset0:12 offset1:13
	s_and_saveexec_b64 s[4:5], s[12:13]
	ds_write_b32 v162, v163 offset:1280
	s_mov_b64 exec, s[4:5]
	s_waitcnt lgkmcnt(9)
	v_pk_fma_f32 v[58:59], v[198:199], v[50:51], v[58:59] op_sel_hi:[0,1,1]
	v_pk_fma_f32 v[72:73], v[198:199], v[52:53], v[72:73] op_sel_hi:[0,1,1]
	s_waitcnt lgkmcnt(7)
	v_pk_fma_f32 v[66:67], v[66:67], v[42:43], v[58:59]
	v_pk_fma_f32 v[64:65], v[64:65], v[44:45], v[72:73]
	v_pk_fma_f32 v[212:213], v[198:199], v[54:55], v[212:213] op_sel_hi:[0,1,1]
	v_pk_fma_f32 v[250:251], v[198:199], v[56:57], v[250:251] op_sel_hi:[0,1,1]
	v_pk_fma_f32 v[62:63], v[62:63], v[46:47], v[212:213]
	v_pk_fma_f32 v[60:61], v[60:61], v[48:49], v[250:251]
	ds_read_b128 v[50:53], v0 offset:23552
	ds_read_b128 v[54:57], v0 offset:23568
	ds_read_b128 v[42:45], v0 offset:7168
	ds_read_b128 v[46:49], v0 offset:7184
	s_waitcnt lgkmcnt(9)
	v_pk_fma_f32 v[58:59], v[66:67], v[154:155], 0 op_sel_hi:[1,1,0]
	v_pk_fma_f32 v[72:73], v[64:65], v[156:157], 0 op_sel_hi:[1,1,0]
	v_pk_fma_f32 v[58:59], v[62:63], v[246:247], v[58:59]
	v_pk_fma_f32 v[72:73], v[60:61], v[248:249], v[72:73]
	ds_read_b128 v[154:157], v0 offset:3072
	ds_read_b128 v[246:249], v0 offset:3088
	v_add_f32_e32 v207, v58, v59
	v_add_f32_e32 v209, v72, v73
	ds_read_b128 v[200:203], v0 offset:19712
	ds_read_b128 v[230:233], v0 offset:19728
	s_waitcnt lgkmcnt(11)
	v_pk_mul_f32 v[34:35], v[66:67], v[34:35]
	v_pk_mul_f32 v[36:37], v[64:65], v[36:37]
	v_pk_fma_f32 v[34:35], v[62:63], v[38:39], v[34:35]
	v_pk_fma_f32 v[36:37], v[60:61], v[40:41], v[36:37]
	v_add_f32_e32 v198, v34, v35
	v_add_f32_e32 v199, v36, v37
	v_add_f32_e32 v207, v207, v209
	v_add_f32_e32 v198, v198, v199
	s_waitcnt lgkmcnt(8)
; DI float oct_sum(float v) { v += dpp_f<0xB1>(v); v += dpp_f<0x4E>(v); v += dpp_f<0x141>(v); return v; }
; DI void scan_item(const Params& p, int b, int h, int half, char* smem, unsigned* pgen, unsigned kp) {
;     ...
; #pragma unroll 1
;     for (int sg = 0; sg < SC; sg += 4) {
;       float yy[4];
; #pragma unroll
;       for (int s4 = 0; s4 < 4; ++s4) {
;         const int s = sg + s4;
;         const f32x2* a2 = (const f32x2*)(Al + s * 64 + cg * 8);
;         const f32x2* w2 = (const f32x2*)(Wl + s * 64 + cg * 8);
;         const f32x2* b2 = (const f32x2*)(Bl + s * 64 + cg * 8);
;         const f32x2* k2 = (const f32x2*)(Kl + s * 64 + cg * 8);
;         const f32x2* r2 = (const f32x2*)(Rl + s * 64 + cg * 8);
;         f32x2 o[20];
; #pragma unroll
;         for (int i = 0; i < 4; ++i) { o[i] = a2[i]; o[4 + i] = w2[i]; o[8 + i] = b2[i]; o[12 + i] = k2[i]; o[16 + i] = r2[i]; }
;         const float vr = Vl[s * 64 + 32 * half + rp];
;         f32x2 p0 = St[0] * o[0], p1 = St[1] * o[1];
;         p0 = __builtin_elementwise_fma(St[2], o[2], p0); p1 = __builtin_elementwise_fma(St[3], o[3], p1);
;         const float sa = oct_sum((p0.x + p0.y) + (p1.x + p1.y));
;         const f32x2 sv = {sa, sa}, vv = {vr, vr};
;         f32x2 y0 = {0.f, 0.f}, y1 = {0.f, 0.f};
; #pragma unroll
;         for (int i = 0; i < 4; i += 2) {
;           St[i] = __builtin_elementwise_fma(St[i], o[4 + i], __builtin_elementwise_fma(sv, o[8 + i], vv * o[12 + i]));
;           St[i + 1] = __builtin_elementwise_fma(St[i + 1], o[5 + i], __builtin_elementwise_fma(sv, o[9 + i], vv * o[13 + i]));
;           y0 = __builtin_elementwise_fma(St[i], o[16 + i], y0);
;           y1 = __builtin_elementwise_fma(St[i + 1], o[17 + i], y1);
;         }
;         yy[s4] = oct_sum((y0.x + y0.y) + (y1.x + y1.y));
;       }
;       if (cg == 0) {
; #pragma unroll
;         for (int s4 = 0; s4 < 4; ++s4) Yl[(sg + s4) * 32 + rp] = yy[s4];
;       }
	v_pk_mul_f32 v[58:59], v[68:69], v[158:159] op_sel_hi:[1,0]
	v_pk_mul_f32 v[72:73], v[70:71], v[158:159] op_sel_hi:[1,0]
	ds_read_b128 v[68:71], v0 offset:11520
	v_add_f32_dpp v198, v198, v198 quad_perm:[1,0,3,2] row_mask:0xf bank_mask:0xf bound_ctrl:1
	v_add_f32_dpp v207, v207, v207 quad_perm:[1,0,3,2] row_mask:0xf bank_mask:0xf bound_ctrl:1
	v_pk_mul_f32 v[212:213], v[150:151], v[158:159] op_sel_hi:[1,0]
	v_add_f32_dpp v198, v198, v198 quad_perm:[2,3,0,1] row_mask:0xf bank_mask:0xf bound_ctrl:1
	v_add_f32_dpp v207, v207, v207 quad_perm:[2,3,0,1] row_mask:0xf bank_mask:0xf bound_ctrl:1
	v_pk_mul_f32 v[250:251], v[152:153], v[158:159] op_sel_hi:[1,0]
	ds_read_b128 v[150:153], v0 offset:11536
	v_add_f32_dpp v198, v198, v198 row_half_mirror row_mask:0xf bank_mask:0xf bound_ctrl:1
	v_add_f32_dpp v205, v207, v207 row_half_mirror row_mask:0xf bank_mask:0xf bound_ctrl:1
	s_and_saveexec_b64 s[4:5], s[12:13]
	ds_write_b32 v162, v205 offset:1408
	s_mov_b64 exec, s[4:5]
	s_waitcnt lgkmcnt(8)
	v_pk_fma_f32 v[58:59], v[198:199], v[50:51], v[58:59] op_sel_hi:[0,1,1]
	v_pk_fma_f32 v[72:73], v[198:199], v[52:53], v[72:73] op_sel_hi:[0,1,1]
	s_waitcnt lgkmcnt(6)
	v_pk_fma_f32 v[66:67], v[66:67], v[42:43], v[58:59]
	v_pk_fma_f32 v[64:65], v[64:65], v[44:45], v[72:73]
	v_pk_fma_f32 v[212:213], v[198:199], v[54:55], v[212:213] op_sel_hi:[0,1,1]
	v_pk_fma_f32 v[250:251], v[198:199], v[56:57], v[250:251] op_sel_hi:[0,1,1]
	v_pk_fma_f32 v[62:63], v[62:63], v[46:47], v[212:213]
	v_pk_fma_f32 v[60:61], v[60:61], v[48:49], v[250:251]
	ds_read_b128 v[50:53], v0 offset:23808
	ds_read_b128 v[54:57], v0 offset:23824
	ds_read_b128 v[42:45], v0 offset:7424
	ds_read_b128 v[46:49], v0 offset:7440
	s_waitcnt lgkmcnt(8)
	v_pk_fma_f32 v[58:59], v[66:67], v[154:155], 0 op_sel_hi:[1,1,0]
	v_pk_fma_f32 v[72:73], v[64:65], v[156:157], 0 op_sel_hi:[1,1,0]
	v_pk_fma_f32 v[58:59], v[62:63], v[246:247], v[58:59]
	v_pk_fma_f32 v[72:73], v[60:61], v[248:249], v[72:73]
	ds_read_b128 v[154:157], v0 offset:3328
	ds_read_b128 v[246:249], v0 offset:3344
	v_add_f32_e32 v207, v58, v59
	v_add_f32_e32 v209, v72, v73
	ds_read_b128 v[34:37], v0 offset:19968
	ds_read_b128 v[38:41], v0 offset:19984
	s_waitcnt lgkmcnt(10)
	v_pk_mul_f32 v[200:201], v[66:67], v[200:201]
	v_pk_mul_f32 v[202:203], v[64:65], v[202:203]
	v_pk_fma_f32 v[200:201], v[62:63], v[230:231], v[200:201]
	v_pk_fma_f32 v[202:203], v[60:61], v[232:233], v[202:203]
	v_add_f32_e32 v198, v200, v201
	v_add_f32_e32 v199, v202, v203
	v_add_f32_e32 v207, v207, v209
	v_add_f32_e32 v198, v198, v199
	s_waitcnt lgkmcnt(8)
	v_mov_b32_e32 v232, v159
	v_pk_mul_f32 v[58:59], v[68:69], v[232:233] op_sel_hi:[1,0]
	v_pk_mul_f32 v[72:73], v[70:71], v[232:233] op_sel_hi:[1,0]
	ds_read_b128 v[68:71], v0 offset:11776
	v_add_f32_dpp v198, v198, v198 quad_perm:[1,0,3,2] row_mask:0xf bank_mask:0xf bound_ctrl:1
	v_add_f32_dpp v207, v207, v207 quad_perm:[1,0,3,2] row_mask:0xf bank_mask:0xf bound_ctrl:1
	v_pk_mul_f32 v[212:213], v[150:151], v[232:233] op_sel_hi:[1,0]
	v_add_f32_dpp v198, v198, v198 quad_perm:[2,3,0,1] row_mask:0xf bank_mask:0xf bound_ctrl:1
	v_add_f32_dpp v207, v207, v207 quad_perm:[2,3,0,1] row_mask:0xf bank_mask:0xf bound_ctrl:1
	v_pk_mul_f32 v[250:251], v[152:153], v[232:233] op_sel_hi:[1,0]
	ds_read_b128 v[150:153], v0 offset:11792
	v_add_f32_dpp v198, v198, v198 row_half_mirror row_mask:0xf bank_mask:0xf bound_ctrl:1
	v_add_f32_dpp v163, v207, v207 row_half_mirror row_mask:0xf bank_mask:0xf bound_ctrl:1
	ds_read2st64_b32 v[158:159], v161 offset0:14 offset1:15
	s_and_saveexec_b64 s[4:5], s[12:13]
	ds_write_b32 v162, v163 offset:1536
	s_mov_b64 exec, s[4:5]
	s_waitcnt lgkmcnt(9)
	v_pk_fma_f32 v[58:59], v[198:199], v[50:51], v[58:59] op_sel_hi:[0,1,1]
	v_pk_fma_f32 v[72:73], v[198:199], v[52:53], v[72:73] op_sel_hi:[0,1,1]
	s_waitcnt lgkmcnt(7)
	v_pk_fma_f32 v[66:67], v[66:67], v[42:43], v[58:59]
	v_pk_fma_f32 v[64:65], v[64:65], v[44:45], v[72:73]
	v_pk_fma_f32 v[212:213], v[198:199], v[54:55], v[212:213] op_sel_hi:[0,1,1]
	v_pk_fma_f32 v[250:251], v[198:199], v[56:57], v[250:251] op_sel_hi:[0,1,1]
	v_pk_fma_f32 v[62:63], v[62:63], v[46:47], v[212:213]
	v_pk_fma_f32 v[60:61], v[60:61], v[48:49], v[250:251]
	ds_read_b128 v[50:53], v0 offset:24064
	ds_read_b128 v[54:57], v0 offset:24080
	ds_read_b128 v[42:45], v0 offset:7680
	ds_read_b128 v[46:49], v0 offset:7696
	s_waitcnt lgkmcnt(9)
	v_pk_fma_f32 v[58:59], v[66:67], v[154:155], 0 op_sel_hi:[1,1,0]
	v_pk_fma_f32 v[72:73], v[64:65], v[156:157], 0 op_sel_hi:[1,1,0]
	v_pk_fma_f32 v[58:59], v[62:63], v[246:247], v[58:59]
	v_pk_fma_f32 v[72:73], v[60:61], v[248:249], v[72:73]
	ds_read_b128 v[154:157], v0 offset:3584
	ds_read_b128 v[246:249], v0 offset:3600
	v_add_f32_e32 v207, v58, v59
	v_add_f32_e32 v209, v72, v73
	ds_read_b128 v[200:203], v0 offset:20224
	ds_read_b128 v[230:233], v0 offset:20240
	s_waitcnt lgkmcnt(11)
; DI float oct_sum(float v) { v += dpp_f<0xB1>(v); v += dpp_f<0x4E>(v); v += dpp_f<0x141>(v); return v; }
; DI void scan_item(const Params& p, int b, int h, int half, char* smem, unsigned* pgen, unsigned kp) {
;     ...
; #pragma unroll 1
;     for (int sg = 0; sg < SC; sg += 4) {
;       float yy[4];
; #pragma unroll
;       for (int s4 = 0; s4 < 4; ++s4) {
;         const int s = sg + s4;
;         const f32x2* a2 = (const f32x2*)(Al + s * 64 + cg * 8);
;         const f32x2* w2 = (const f32x2*)(Wl + s * 64 + cg * 8);
;         const f32x2* b2 = (const f32x2*)(Bl + s * 64 + cg * 8);
;         const f32x2* k2 = (const f32x2*)(Kl + s * 64 + cg * 8);
;         const f32x2* r2 = (const f32x2*)(Rl + s * 64 + cg * 8);
;         f32x2 o[20];
; #pragma unroll
;         for (int i = 0; i < 4; ++i) { o[i] = a2[i]; o[4 + i] = w2[i]; o[8 + i] = b2[i]; o[12 + i] = k2[i]; o[16 + i] = r2[i]; }
;         const float vr = Vl[s * 64 + 32 * half + rp];
;         f32x2 p0 = St[0] * o[0], p1 = St[1] * o[1];
;         p0 = __builtin_elementwise_fma(St[2], o[2], p0); p1 = __builtin_elementwise_fma(St[3], o[3], p1);
;         const float sa = oct_sum((p0.x + p0.y) + (p1.x + p1.y));
;         const f32x2 sv = {sa, sa}, vv = {vr, vr};
;         f32x2 y0 = {0.f, 0.f}, y1 = {0.f, 0.f};
; #pragma unroll
;         for (int i = 0; i < 4; i += 2) {
;           St[i] = __builtin_elementwise_fma(St[i], o[4 + i], __builtin_elementwise_fma(sv, o[8 + i], vv * o[12 + i]));
;           St[i + 1] = __builtin_elementwise_fma(St[i + 1], o[5 + i], __builtin_elementwise_fma(sv, o[9 + i], vv * o[13 + i]));
;           y0 = __builtin_elementwise_fma(St[i], o[16 + i], y0);
;           y1 = __builtin_elementwise_fma(St[i + 1], o[17 + i], y1);
;         }
;         yy[s4] = oct_sum((y0.x + y0.y) + (y1.x + y1.y));
;       }
;       if (cg == 0) {
; #pragma unroll
;         for (int s4 = 0; s4 < 4; ++s4) Yl[(sg + s4) * 32 + rp] = yy[s4];
;       }
	v_pk_mul_f32 v[34:35], v[66:67], v[34:35]
	v_pk_mul_f32 v[36:37], v[64:65], v[36:37]
	v_pk_fma_f32 v[34:35], v[62:63], v[38:39], v[34:35]
	v_pk_fma_f32 v[36:37], v[60:61], v[40:41], v[36:37]
	v_add_f32_e32 v198, v34, v35
	v_add_f32_e32 v199, v36, v37
	v_add_f32_e32 v207, v207, v209
	v_add_f32_e32 v198, v198, v199
	s_waitcnt lgkmcnt(8)
	v_pk_mul_f32 v[58:59], v[68:69], v[158:159] op_sel_hi:[1,0]
	v_pk_mul_f32 v[72:73], v[70:71], v[158:159] op_sel_hi:[1,0]
	ds_read_b128 v[68:71], v0 offset:12032
	v_add_f32_dpp v198, v198, v198 quad_perm:[1,0,3,2] row_mask:0xf bank_mask:0xf bound_ctrl:1
	v_add_f32_dpp v207, v207, v207 quad_perm:[1,0,3,2] row_mask:0xf bank_mask:0xf bound_ctrl:1
	v_pk_mul_f32 v[212:213], v[150:151], v[158:159] op_sel_hi:[1,0]
	v_add_f32_dpp v198, v198, v198 quad_perm:[2,3,0,1] row_mask:0xf bank_mask:0xf bound_ctrl:1
	v_add_f32_dpp v207, v207, v207 quad_perm:[2,3,0,1] row_mask:0xf bank_mask:0xf bound_ctrl:1
	v_pk_mul_f32 v[250:251], v[152:153], v[158:159] op_sel_hi:[1,0]
	ds_read_b128 v[150:153], v0 offset:12048
	v_add_f32_dpp v198, v198, v198 row_half_mirror row_mask:0xf bank_mask:0xf bound_ctrl:1
	v_add_f32_dpp v205, v207, v207 row_half_mirror row_mask:0xf bank_mask:0xf bound_ctrl:1
	s_and_saveexec_b64 s[4:5], s[12:13]
	ds_write_b32 v162, v205 offset:1664
	s_mov_b64 exec, s[4:5]
	s_waitcnt lgkmcnt(8)
	v_pk_fma_f32 v[58:59], v[198:199], v[50:51], v[58:59] op_sel_hi:[0,1,1]
	v_pk_fma_f32 v[72:73], v[198:199], v[52:53], v[72:73] op_sel_hi:[0,1,1]
	s_waitcnt lgkmcnt(6)
	v_pk_fma_f32 v[66:67], v[66:67], v[42:43], v[58:59]
	v_pk_fma_f32 v[64:65], v[64:65], v[44:45], v[72:73]
	v_pk_fma_f32 v[212:213], v[198:199], v[54:55], v[212:213] op_sel_hi:[0,1,1]
	v_pk_fma_f32 v[250:251], v[198:199], v[56:57], v[250:251] op_sel_hi:[0,1,1]
	v_pk_fma_f32 v[62:63], v[62:63], v[46:47], v[212:213]
	v_pk_fma_f32 v[60:61], v[60:61], v[48:49], v[250:251]
	ds_read_b128 v[50:53], v0 offset:24320
	ds_read_b128 v[54:57], v0 offset:24336
	ds_read_b128 v[42:45], v0 offset:7936
	ds_read_b128 v[46:49], v0 offset:7952
	s_waitcnt lgkmcnt(8)
	v_pk_fma_f32 v[58:59], v[66:67], v[154:155], 0 op_sel_hi:[1,1,0]
	v_pk_fma_f32 v[72:73], v[64:65], v[156:157], 0 op_sel_hi:[1,1,0]
	v_pk_fma_f32 v[58:59], v[62:63], v[246:247], v[58:59]
	v_pk_fma_f32 v[72:73], v[60:61], v[248:249], v[72:73]
	ds_read_b128 v[154:157], v0 offset:3840
	ds_read_b128 v[246:249], v0 offset:3856
	v_add_f32_e32 v207, v58, v59
	v_add_f32_e32 v209, v72, v73
	s_waitcnt lgkmcnt(8)
	v_pk_mul_f32 v[200:201], v[66:67], v[200:201]
	v_pk_mul_f32 v[202:203], v[64:65], v[202:203]
	v_pk_fma_f32 v[200:201], v[62:63], v[230:231], v[200:201]
	v_pk_fma_f32 v[202:203], v[60:61], v[232:233], v[202:203]
	v_add_f32_e32 v198, v200, v201
	v_add_f32_e32 v199, v202, v203
	v_add_f32_e32 v207, v207, v209
	v_add_f32_e32 v198, v198, v199
	s_waitcnt lgkmcnt(6)
	v_mov_b32_e32 v232, v159
	v_pk_mul_f32 v[58:59], v[68:69], v[232:233] op_sel_hi:[1,0]
	v_pk_mul_f32 v[72:73], v[70:71], v[232:233] op_sel_hi:[1,0]
	v_add_f32_dpp v198, v198, v198 quad_perm:[1,0,3,2] row_mask:0xf bank_mask:0xf bound_ctrl:1
	v_add_f32_dpp v207, v207, v207 quad_perm:[1,0,3,2] row_mask:0xf bank_mask:0xf bound_ctrl:1
	v_pk_mul_f32 v[212:213], v[150:151], v[232:233] op_sel_hi:[1,0]
	v_add_f32_dpp v198, v198, v198 quad_perm:[2,3,0,1] row_mask:0xf bank_mask:0xf bound_ctrl:1
	v_add_f32_dpp v207, v207, v207 quad_perm:[2,3,0,1] row_mask:0xf bank_mask:0xf bound_ctrl:1
	v_pk_mul_f32 v[250:251], v[152:153], v[232:233] op_sel_hi:[1,0]
	v_add_f32_dpp v198, v198, v198 row_half_mirror row_mask:0xf bank_mask:0xf bound_ctrl:1
	v_add_f32_dpp v163, v207, v207 row_half_mirror row_mask:0xf bank_mask:0xf bound_ctrl:1
	s_and_saveexec_b64 s[4:5], s[12:13]
	ds_write_b32 v162, v163 offset:1792
	s_mov_b64 exec, s[4:5]
	s_waitcnt lgkmcnt(4)
	v_pk_fma_f32 v[58:59], v[198:199], v[50:51], v[58:59] op_sel_hi:[0,1,1]
	v_pk_fma_f32 v[72:73], v[198:199], v[52:53], v[72:73] op_sel_hi:[0,1,1]
	s_waitcnt lgkmcnt(2)
	v_pk_fma_f32 v[66:67], v[66:67], v[42:43], v[58:59]
	v_pk_fma_f32 v[64:65], v[64:65], v[44:45], v[72:73]
	v_pk_fma_f32 v[212:213], v[198:199], v[54:55], v[212:213] op_sel_hi:[0,1,1]
	v_pk_fma_f32 v[250:251], v[198:199], v[56:57], v[250:251] op_sel_hi:[0,1,1]
	v_pk_fma_f32 v[62:63], v[62:63], v[46:47], v[212:213]
	v_pk_fma_f32 v[60:61], v[60:61], v[48:49], v[250:251]
	s_waitcnt lgkmcnt(0)
	v_pk_fma_f32 v[58:59], v[66:67], v[154:155], 0 op_sel_hi:[1,1,0]
	v_pk_fma_f32 v[72:73], v[64:65], v[156:157], 0 op_sel_hi:[1,1,0]
	v_pk_fma_f32 v[58:59], v[62:63], v[246:247], v[58:59]
	v_pk_fma_f32 v[72:73], v[60:61], v[248:249], v[72:73]
	v_add_f32_e32 v207, v58, v59
	v_add_f32_e32 v209, v72, v73
	v_add_f32_e32 v207, v207, v209
	s_nop 1
	v_add_f32_dpp v207, v207, v207 quad_perm:[1,0,3,2] row_mask:0xf bank_mask:0xf bound_ctrl:1
	s_nop 1
	v_add_f32_dpp v207, v207, v207 quad_perm:[2,3,0,1] row_mask:0xf bank_mask:0xf bound_ctrl:1
	s_nop 1
	v_add_f32_dpp v205, v207, v207 row_half_mirror row_mask:0xf bank_mask:0xf bound_ctrl:1
	s_and_saveexec_b64 s[4:5], s[12:13]
	ds_write_b32 v162, v205 offset:1920
	s_mov_b64 exec, s[4:5]
